# P1 epilogue z/kv/conv stores issued with the nt (streaming) cache policy so the 281 MB of z do not displace A/B tiles in L2
# baseline (speedup 1.0000x reference)
;     __device__ __forceinline__ void operator()(const f32x4 (&acc)[2][2][4][2], const Unit& u, int wr, int wc, int fr, int fq) const {
;         const int pn = u.pn;
;         const bool do_rope = (pn < 6) && ((wc & 1) == 0);
;         const bool is_kv = (pn >= 3 && pn < 9);
;         const int kvsel = is_kv ? (pn - 3) / 3 : 0;
;         const int g = is_kv ? (pn - 3) % 3 : 0;
;         const int W = 128 << (2 * g);
;         const size_t okp = g == 0 ? O_KV128_P : (g == 1 ? O_KV512_P : O_KV2048_P);
;         const size_t oks = g == 0 ? O_KV128_S : (g == 1 ? O_KV512_S : O_KV2048_S);
;         const bool is_conv = (pn >= 9 && pn < 17);
;         const float sgn = fq == 0 ? -1.f : 1.f;
; #pragma unroll
;         for (int ai = 0; ai < 2; ++ai)
; #pragma unroll
;             for (int m = 0; m < 4; ++m) {
;                 const int row = u.pm * BM + ai * HALF + wr * 64 + m * 16 + fr;
;                 const bool isP = row < MP, isS = (row >= MP) && (row < MT);
;                 const int b = isP ? (row >> 12) : (row - MP);
;                 const int t = row & 4095;
;                 float cosv[8], sinv[8];
;                 if (do_rope) {
;                     const f32x4* cs = (const f32x4*)(rope + (size_t)(isP ? t : 4096) * 16);
; #pragma unroll
;                     for (int q = 0; q < 4; ++q) { const f32x4 c = cs[q]; cosv[2 * q] = c[0]; sinv[2 * q] = c[1]; cosv[2 * q + 1] = c[2]; sinv[2 * q + 1] = c[3]; }
;                 }
; #pragma unroll
;                 for (int bj = 0; bj < 2; ++bj) {
;                     f32x4 v0 = acc[ai][bj][m][0], v1 = acc[ai][bj][m][1];
;                     const int cit = bj * HALF + wc * 32 + fq * 8;
;                     if (do_rope) {
; #pragma unroll
;                         for (int j = 0; j < 4; ++j) {
;                             const float p0 = __shfl_xor(v0[j], 16), p1 = __shfl_xor(v1[j], 16);
;                             const float r0 = v0[j] * cosv[j] + sgn * p0 * sinv[j], r1 = v1[j] * cosv[4 + j] + sgn * p1 * sinv[4 + j];
;                             v0[j] = fq < 2 ? r0 : v0[j]; v1[j] = fq < 2 ? r1 : v1[j];
;                         }
;                     }
;                     if (pn < 3) { v0 = v0 * QSCALE; v1 = v1 * QSCALE; }
;                     u32x4 w; w.x = cvt_pk_bf16(v0[0], v0[1]); w.y = cvt_pk_bf16(v0[2], v0[3]); w.z = cvt_pk_bf16(v1[0], v1[1]); w.w = cvt_pk_bf16(v1[2], v1[3]);
.LBB0_137:
	s_add_i32 s22, s48, -3
	s_add_i32 s4, s48, -6
	s_cmp_lt_u32 s22, 3
	s_cselect_b32 s1, s22, s4
	s_cmp_lt_u32 s22, 6
	s_cselect_b64 s[92:93], -1, 0
	s_and_b64 s[10:11], s[92:93], exec
	s_cselect_b32 s11, s1, 0
	s_lshl_b32 s56, s11, 1
	s_lshl_b32 s57, 0x80, s56
	s_add_i32 s56, s56, 7
	s_ashr_i32 s1, s14, 12
	s_add_i32 s15, s57, 0xfffff000
	s_lshl_b32 s10, s1, s56
	s_sub_i32 s29, 0x1000, s57
	s_add_i32 s57, s57, -1
	s_add_i32 s10, s10, s15
	s_cmp_lt_u32 s4, 3
	s_cselect_b32 s4, 0x400, 0
	s_cmp_eq_u32 s11, 1
	s_mov_b32 s12, 0x1248000
	s_mov_b32 s13, 0x1348000
	s_cselect_b32 s12, s12, 0x1b48000
	s_cselect_b32 s13, s13, 0x1f48000
	s_cmp_eq_u32 s11, 0
	s_cselect_b32 s27, 0x1008000, s12
	s_cselect_b32 s31, 0x1048000, s13
	s_cmp_lt_i32 s48, 3
	s_cselect_b64 s[44:45], -1, 0
	s_lshl_b32 s18, s48, 8
	v_add_u32_e32 v52, 0xffffc000, v187
	v_mov_b32_e32 v53, s1
	v_pk_mul_f32 v[170:171], v[140:141], s[8:9] op_sel_hi:[1,0]
	s_ashr_i32 s19, s18, 31
	v_cndmask_b32_e64 v174, v52, v53, s[46:47]
	s_cmpk_lg_i32 s14, 0x4000
	v_cmp_le_u32_e64 s[50:51], s29, v142
	v_add_u32_e32 v52, s10, v142
	v_lshlrev_b32_e32 v142, s56, v174
	v_cndmask_b32_e64 v141, v141, v171, s[44:45]
	v_cndmask_b32_e64 v140, v140, v170, s[44:45]
	v_mov_b64_e32 v[170:171], s[2:3]
	s_cselect_b64 s[12:13], -1, 0
	s_cmp_gt_u32 s22, 5
	v_add_u32_e32 v168, s57, v142
	v_mad_i64_i32 v[170:171], s[22:23], v187, s9, v[170:171]
	v_ashrrev_i32_e32 v53, 31, v52
	v_ashrrev_i32_e32 v169, 31, v168
	v_pk_mul_f32 v[172:173], v[134:135], s[8:9] op_sel_hi:[1,0]
	v_pk_mul_f32 v[176:177], v[136:137], s[8:9] op_sel_hi:[1,0]
	v_pk_mul_f32 v[178:179], v[138:139], s[8:9] op_sel_hi:[1,0]
	v_lshl_add_u64 v[170:171], s[18:19], 1, v[170:171]
	v_lshlrev_b32_e32 v142, 1, v158
	v_lshlrev_b64 v[52:53], 11, v[52:53]
	v_lshlrev_b64 v[168:169], 11, v[168:169]
	v_cndmask_b32_e64 v139, v139, v179, s[44:45]
	v_cndmask_b32_e64 v138, v138, v178, s[44:45]
	v_cndmask_b32_e64 v137, v137, v177, s[44:45]
	v_cndmask_b32_e64 v136, v136, v176, s[44:45]
	v_cndmask_b32_e64 v135, v135, v173, s[44:45]
	v_cndmask_b32_e64 v134, v134, v172, s[44:45]
	v_lshl_add_u64 v[170:171], v[170:171], 0, v[142:143]
	v_cvt_pk_bf16_f32 v188, v134, v135
	v_cvt_pk_bf16_f32 v189, v136, v137
	v_cvt_pk_bf16_f32 v190, v138, v139
	v_cvt_pk_bf16_f32 v191, v140, v141
	global_store_dwordx4 v[170:171], v[188:191], off nt
	s_cbranch_scc1 .LBB0_143
	s_and_b64 s[22:23], s[46:47], s[50:51]
	s_xor_b64 s[22:23], s[22:23], -1
	s_and_saveexec_b64 s[52:53], s[22:23]
	s_xor_b64 s[52:53], exec, s[52:53]
	s_cbranch_execnz .LBB0_304
	s_andn2_saveexec_b64 s[52:53], s[52:53]
	s_cbranch_execnz .LBB0_305

;     __device__ __forceinline__ void operator()(const f32x4 (&acc)[2][2][4][2], const Unit& u, int wr, int wc, int fr, int fq) const {
;     ...
;                     if (is_kv) {
;                         float* dst = nullptr;
;                         if (isP && t >= 4096 - W) dst = out + okp + ((size_t)(b * W + t - (4096 - W)) * 2 + kvsel) * 256 + cit;
;                         else if (isS) dst = out + oks + ((size_t)(b * W + W - 1) * 2 + kvsel) * 256 + cit;
;                         if (dst) { *(f32x4*)dst = v0; *(f32x4*)(dst + 4) = v1; }
.LBB0_141:
	global_store_dwordx4 v[172:173], v[134:137], off nt
	global_store_dwordx4 v[172:173], v[138:141], off offset:16 nt

;     __device__ __forceinline__ void operator()(const f32x4 (&acc)[2][2][4][2], const Unit& u, int wr, int wc, int fr, int fq) const {
;     ...
;                     if (is_conv) {
;                         const int cc = pn * BM + cit - ZMQ;
;                         float* dst = nullptr;
;                         if (isP && t >= 4093) dst = out + O_CONV_P + (size_t)(b * 3 + t - 4093) * 2048 + cc;
;                         else if (isS) dst = out + O_CONV_S + (size_t)(b * 3 + 2) * 2048 + cc;
;                         if (dst) { *(f32x4*)dst = v0; *(f32x4*)(dst + 4) = v1; }
.LBB0_143:
	v_lshl_add_u32 v172, v174, 1, v174
	v_ashrrev_i32_e32 v173, 31, v172
	s_add_i32 s11, s48, -9
	v_lshlrev_b64 v[172:173], 13, v[172:173]
	s_cmp_lt_u32 s11, 8
	s_mov_b64 s[22:23], 0x4000
	s_cselect_b64 s[52:53], -1, 0
	s_cmp_gt_u32 s11, 7
	v_lshl_add_u64 v[172:173], v[172:173], 0, s[22:23]
	s_cbranch_scc1 .LBB0_147
	v_or_b32_e32 v174, s18, v158
	v_lshl_add_u64 v[176:177], s[96:97], 0, v[172:173]
	v_mov_b32_e32 v175, v143
	v_lshl_add_u64 v[174:175], v[174:175], 2, v[176:177]
	s_mov_b64 s[22:23], 0xfd35c00
	v_lshl_add_u64 v[176:177], v[174:175], 0, s[22:23]
	v_cmp_ne_u64_e32 vcc, 0, v[176:177]
	s_xor_b64 s[22:23], s[12:13], -1
	s_and_b64 s[22:23], s[22:23], vcc
	s_and_saveexec_b64 s[48:49], s[22:23]
	s_cbranch_execz .LBB0_146
	global_store_dwordx4 v[176:177], v[134:137], off nt
	s_nop 1
	v_add_co_u32_e32 v134, vcc, 0xfd35000, v174
	s_nop 1
	v_addc_co_u32_e32 v135, vcc, 0, v175, vcc
	global_store_dwordx4 v[134:135], v[138:141], off offset:3088 nt

; __device__ __forceinline__ unsigned cvt_pk_bf16(float lo, float hi) { unsigned r; asm volatile("v_cvt_pk_bf16_f32 %0, %1, %2" : "=v"(r) : "v"(lo), "v"(hi)); return r; }
;     __device__ __forceinline__ void operator()(const f32x4 (&acc)[2][2][4][2], const Unit& u, int wr, int wc, int fr, int fq) const {
;     ...
;                     f32x4 v0 = acc[ai][bj][m][0], v1 = acc[ai][bj][m][1];
;                     const int cit = bj * HALF + wc * 32 + fq * 8;
;                     if (do_rope) {
; #pragma unroll
;                         for (int j = 0; j < 4; ++j) {
;                             const float p0 = __shfl_xor(v0[j], 16), p1 = __shfl_xor(v1[j], 16);
;                             const float r0 = v0[j] * cosv[j] + sgn * p0 * sinv[j], r1 = v1[j] * cosv[4 + j] + sgn * p1 * sinv[4 + j];
;                             v0[j] = fq < 2 ? r0 : v0[j]; v1[j] = fq < 2 ? r1 : v1[j];
;                         }
;                     }
;                     if (pn < 3) { v0 = v0 * QSCALE; v1 = v1 * QSCALE; }
;                     u32x4 w; w.x = cvt_pk_bf16(v0[0], v0[1]); w.y = cvt_pk_bf16(v0[2], v0[3]); w.z = cvt_pk_bf16(v1[0], v1[1]); w.w = cvt_pk_bf16(v1[2], v1[3]);
;                     *(u32x4*)(Z + (size_t)row * NZ + pn * BM + cit) = w;
.LBB0_149:
	v_pk_mul_f32 v[138:139], v[130:131], s[8:9] op_sel_hi:[1,0]
	v_pk_mul_f32 v[134:135], v[126:127], s[8:9] op_sel_hi:[1,0]
	v_pk_mul_f32 v[136:137], v[128:129], s[8:9] op_sel_hi:[1,0]
	v_pk_mul_f32 v[140:141], v[132:133], s[8:9] op_sel_hi:[1,0]
	v_cndmask_b32_e64 v130, v130, v138, s[44:45]
	v_cndmask_b32_e64 v138, 0, 1, s[92:93]
	v_cndmask_b32_e64 v133, v133, v141, s[44:45]
	v_cndmask_b32_e64 v132, v132, v140, s[44:45]
	v_cndmask_b32_e64 v131, v131, v139, s[44:45]
	v_cndmask_b32_e64 v129, v129, v137, s[44:45]
	v_cndmask_b32_e64 v128, v128, v136, s[44:45]
	v_cndmask_b32_e64 v127, v127, v135, s[44:45]
	v_cndmask_b32_e64 v126, v126, v134, s[44:45]
	v_cmp_ne_u32_e64 s[48:49], 1, v138
	s_andn2_b64 vcc, exec, s[92:93]
	v_cvt_pk_bf16_f32 v134, v126, v127
	v_cvt_pk_bf16_f32 v135, v128, v129
	v_cvt_pk_bf16_f32 v136, v130, v131
	v_cvt_pk_bf16_f32 v137, v132, v133
	global_store_dwordx4 v[170:171], v[134:137], off offset:256 nt
	s_cbranch_vccnz .LBB0_155
	s_and_b64 s[22:23], s[46:47], s[50:51]
	s_xor_b64 s[22:23], s[22:23], -1
	s_and_saveexec_b64 s[46:47], s[22:23]
	s_xor_b64 s[46:47], exec, s[46:47]
	s_cbranch_execnz .LBB0_306
	s_andn2_saveexec_b64 s[46:47], s[46:47]
	s_cbranch_execnz .LBB0_307

;     __device__ __forceinline__ void operator()(const f32x4 (&acc)[2][2][4][2], const Unit& u, int wr, int wc, int fr, int fq) const {
;     ...
;                     if (is_kv) {
;                         float* dst = nullptr;
;                         if (isP && t >= 4096 - W) dst = out + okp + ((size_t)(b * W + t - (4096 - W)) * 2 + kvsel) * 256 + cit;
;                         else if (isS) dst = out + oks + ((size_t)(b * W + W - 1) * 2 + kvsel) * 256 + cit;
;                         if (dst) { *(f32x4*)dst = v0; *(f32x4*)(dst + 4) = v1; }
.LBB0_153:
	global_store_dwordx4 v[134:135], v[126:129], off nt
	global_store_dwordx4 v[134:135], v[130:133], off offset:16 nt

;     __device__ __forceinline__ void operator()(const f32x4 (&acc)[2][2][4][2], const Unit& u, int wr, int wc, int fr, int fq) const {
;     ...
;                     if (is_conv) {
;                         const int cc = pn * BM + cit - ZMQ;
;                         float* dst = nullptr;
;                         if (isP && t >= 4093) dst = out + O_CONV_P + (size_t)(b * 3 + t - 4093) * 2048 + cc;
;                         else if (isS) dst = out + O_CONV_S + (size_t)(b * 3 + 2) * 2048 + cc;
;                         if (dst) { *(f32x4*)dst = v0; *(f32x4*)(dst + 4) = v1; }
.LBB0_155:
	v_cndmask_b32_e64 v52, 0, 1, s[52:53]
	v_cmp_ne_u32_e64 s[46:47], 1, v52
	s_andn2_b64 vcc, exec, s[52:53]
	s_cbranch_vccnz .LBB0_159
	v_lshl_add_u64 v[52:53], s[96:97], 0, v[172:173]
	v_add_u32_e32 v134, s18, v158
	v_mov_b32_e32 v135, v143
	v_lshl_add_u64 v[52:53], v[134:135], 2, v[52:53]
	s_mov_b64 s[22:23], 0xfd35e00
	v_lshl_add_u64 v[134:135], v[52:53], 0, s[22:23]
	v_cmp_ne_u64_e32 vcc, 0, v[134:135]
	s_xor_b64 s[22:23], s[12:13], -1
	s_and_b64 s[50:51], s[22:23], vcc
	s_and_saveexec_b64 s[22:23], s[50:51]
	s_cbranch_execz .LBB0_158
	s_mov_b64 s[50:51], 0x200
	v_lshl_add_u64 v[52:53], v[52:53], 0, s[50:51]
	v_add_co_u32_e32 v52, vcc, 0xfd35000, v52
	global_store_dwordx4 v[134:135], v[126:129], off nt
	s_nop 0
	v_addc_co_u32_e32 v53, vcc, 0, v53, vcc
	global_store_dwordx4 v[52:53], v[130:133], off offset:3088 nt

; __device__ __forceinline__ unsigned cvt_pk_bf16(float lo, float hi) { unsigned r; asm volatile("v_cvt_pk_bf16_f32 %0, %1, %2" : "=v"(r) : "v"(lo), "v"(hi)); return r; }
;     __device__ __forceinline__ void operator()(const f32x4 (&acc)[2][2][4][2], const Unit& u, int wr, int wc, int fr, int fq) const {
;     ...
;                 const int row = u.pm * BM + ai * HALF + wr * 64 + m * 16 + fr;
;                 const bool isP = row < MP, isS = (row >= MP) && (row < MT);
;                 const int b = isP ? (row >> 12) : (row - MP);
;                 const int t = row & 4095;
;                 float cosv[8], sinv[8];
;                 if (do_rope) {
;                     const f32x4* cs = (const f32x4*)(rope + (size_t)(isP ? t : 4096) * 16);
; #pragma unroll
;                     for (int q = 0; q < 4; ++q) { const f32x4 c = cs[q]; cosv[2 * q] = c[0]; sinv[2 * q] = c[1]; cosv[2 * q + 1] = c[2]; sinv[2 * q + 1] = c[3]; }
;                 }
; #pragma unroll
;                 for (int bj = 0; bj < 2; ++bj) {
;                     f32x4 v0 = acc[ai][bj][m][0], v1 = acc[ai][bj][m][1];
;                     const int cit = bj * HALF + wc * 32 + fq * 8;
;                     if (do_rope) {
; #pragma unroll
;                         for (int j = 0; j < 4; ++j) {
;                             const float p0 = __shfl_xor(v0[j], 16), p1 = __shfl_xor(v1[j], 16);
;                             const float r0 = v0[j] * cosv[j] + sgn * p0 * sinv[j], r1 = v1[j] * cosv[4 + j] + sgn * p1 * sinv[4 + j];
;                             v0[j] = fq < 2 ? r0 : v0[j]; v1[j] = fq < 2 ? r1 : v1[j];
;                         }
;                     }
;                     if (pn < 3) { v0 = v0 * QSCALE; v1 = v1 * QSCALE; }
;                     u32x4 w; w.x = cvt_pk_bf16(v0[0], v0[1]); w.y = cvt_pk_bf16(v0[2], v0[3]); w.z = cvt_pk_bf16(v1[0], v1[1]); w.w = cvt_pk_bf16(v1[2], v1[3]);
;                     *(u32x4*)(Z + (size_t)row * NZ + pn * BM + cit) = w;
.LBB0_163:
	v_add_u32_e32 v53, 0xffffc010, v187
	v_mov_b32_e32 v126, s1
	v_cndmask_b32_e64 v132, v53, v126, s[50:51]
	v_pk_mul_f32 v[130:131], v[118:119], s[8:9] op_sel_hi:[1,0]
	v_lshlrev_b32_e32 v126, s56, v132
	v_cndmask_b32_e64 v119, v119, v131, s[44:45]
	v_cndmask_b32_e64 v118, v118, v130, s[44:45]
	v_mov_b64_e32 v[130:131], s[2:3]
	v_cmp_le_u32_e64 s[52:53], s29, v52
	v_add_u32_e32 v52, s10, v52
	v_add_u32_e32 v126, s57, v126
	v_mad_i64_i32 v[128:129], s[22:23], v128, s9, v[130:131]
	v_ashrrev_i32_e32 v53, 31, v52
	v_ashrrev_i32_e32 v127, 31, v126
	v_pk_mul_f32 v[134:135], v[120:121], s[8:9] op_sel_hi:[1,0]
	v_pk_mul_f32 v[136:137], v[122:123], s[8:9] op_sel_hi:[1,0]
	v_pk_mul_f32 v[138:139], v[124:125], s[8:9] op_sel_hi:[1,0]
	v_lshl_add_u64 v[128:129], s[18:19], 1, v[128:129]
	v_lshlrev_b64 v[52:53], 11, v[52:53]
	v_lshlrev_b64 v[126:127], 11, v[126:127]
	v_cndmask_b32_e64 v125, v125, v139, s[44:45]
	v_cndmask_b32_e64 v124, v124, v138, s[44:45]
	v_cndmask_b32_e64 v123, v123, v137, s[44:45]
	v_cndmask_b32_e64 v122, v122, v136, s[44:45]
	v_cndmask_b32_e64 v121, v121, v135, s[44:45]
	v_cndmask_b32_e64 v120, v120, v134, s[44:45]
	v_lshl_add_u64 v[128:129], v[128:129], 0, v[142:143]
	s_and_b64 vcc, exec, s[48:49]
	v_cvt_pk_bf16_f32 v134, v118, v119
	v_cvt_pk_bf16_f32 v135, v120, v121
	v_cvt_pk_bf16_f32 v136, v122, v123
	v_cvt_pk_bf16_f32 v137, v124, v125
	global_store_dwordx4 v[128:129], v[134:137], off nt
	s_cbranch_vccnz .LBB0_169
	s_and_b64 s[22:23], s[50:51], s[52:53]
	s_xor_b64 s[22:23], s[22:23], -1
	s_and_saveexec_b64 vcc, s[22:23]
	s_xor_b64 vcc, exec, vcc
	s_cbranch_execnz .LBB0_308
	s_andn2_saveexec_b64 vcc, vcc
	s_cbranch_execnz .LBB0_309

;     __device__ __forceinline__ void operator()(const f32x4 (&acc)[2][2][4][2], const Unit& u, int wr, int wc, int fr, int fq) const {
;     ...
;                     if (is_kv) {
;                         float* dst = nullptr;
;                         if (isP && t >= 4096 - W) dst = out + okp + ((size_t)(b * W + t - (4096 - W)) * 2 + kvsel) * 256 + cit;
;                         else if (isS) dst = out + oks + ((size_t)(b * W + W - 1) * 2 + kvsel) * 256 + cit;
;                         if (dst) { *(f32x4*)dst = v0; *(f32x4*)(dst + 4) = v1; }
.LBB0_167:
	global_store_dwordx4 v[130:131], v[118:121], off nt
	global_store_dwordx4 v[130:131], v[122:125], off offset:16 nt

;     __device__ __forceinline__ void operator()(const f32x4 (&acc)[2][2][4][2], const Unit& u, int wr, int wc, int fr, int fq) const {
;     ...
;                     if (is_conv) {
;                         const int cc = pn * BM + cit - ZMQ;
;                         float* dst = nullptr;
;                         if (isP && t >= 4093) dst = out + O_CONV_P + (size_t)(b * 3 + t - 4093) * 2048 + cc;
;                         else if (isS) dst = out + O_CONV_S + (size_t)(b * 3 + 2) * 2048 + cc;
;                         if (dst) { *(f32x4*)dst = v0; *(f32x4*)(dst + 4) = v1; }
.LBB0_169:
	v_lshl_add_u32 v130, v132, 1, v132
	v_ashrrev_i32_e32 v131, 31, v130
	v_lshlrev_b64 v[130:131], 13, v[130:131]
	s_mov_b64 s[22:23], 0x4000
	s_and_b64 vcc, exec, s[46:47]
	v_lshl_add_u64 v[130:131], v[130:131], 0, s[22:23]
	s_cbranch_vccnz .LBB0_173
	v_or_b32_e32 v132, s18, v158
	v_lshl_add_u64 v[134:135], s[96:97], 0, v[130:131]
	v_mov_b32_e32 v133, v143
	v_lshl_add_u64 v[132:133], v[132:133], 2, v[134:135]
	s_mov_b64 s[22:23], 0xfd35c00
	v_lshl_add_u64 v[134:135], v[132:133], 0, s[22:23]
	v_cmp_ne_u64_e32 vcc, 0, v[134:135]
	s_xor_b64 s[22:23], s[12:13], -1
	s_and_b64 vcc, s[22:23], vcc
	s_and_saveexec_b64 s[22:23], vcc
	s_cbranch_execz .LBB0_172
	global_store_dwordx4 v[134:135], v[118:121], off nt
	s_nop 1
	v_add_co_u32_e32 v118, vcc, 0xfd35000, v132
	s_nop 1
	v_addc_co_u32_e32 v119, vcc, 0, v133, vcc
	global_store_dwordx4 v[118:119], v[122:125], off offset:3088 nt

; __device__ __forceinline__ unsigned cvt_pk_bf16(float lo, float hi) { unsigned r; asm volatile("v_cvt_pk_bf16_f32 %0, %1, %2" : "=v"(r) : "v"(lo), "v"(hi)); return r; }
;     __device__ __forceinline__ void operator()(const f32x4 (&acc)[2][2][4][2], const Unit& u, int wr, int wc, int fr, int fq) const {
;     ...
;                     f32x4 v0 = acc[ai][bj][m][0], v1 = acc[ai][bj][m][1];
;                     const int cit = bj * HALF + wc * 32 + fq * 8;
;                     if (do_rope) {
; #pragma unroll
;                         for (int j = 0; j < 4; ++j) {
;                             const float p0 = __shfl_xor(v0[j], 16), p1 = __shfl_xor(v1[j], 16);
;                             const float r0 = v0[j] * cosv[j] + sgn * p0 * sinv[j], r1 = v1[j] * cosv[4 + j] + sgn * p1 * sinv[4 + j];
;                             v0[j] = fq < 2 ? r0 : v0[j]; v1[j] = fq < 2 ? r1 : v1[j];
;                         }
;                     }
;                     if (pn < 3) { v0 = v0 * QSCALE; v1 = v1 * QSCALE; }
;                     u32x4 w; w.x = cvt_pk_bf16(v0[0], v0[1]); w.y = cvt_pk_bf16(v0[2], v0[3]); w.z = cvt_pk_bf16(v1[0], v1[1]); w.w = cvt_pk_bf16(v1[2], v1[3]);
;                     *(u32x4*)(Z + (size_t)row * NZ + pn * BM + cit) = w;
.LBB0_175:
	v_pk_mul_f32 v[118:119], v[110:111], s[8:9] op_sel_hi:[1,0]
	v_pk_mul_f32 v[120:121], v[112:113], s[8:9] op_sel_hi:[1,0]
	v_pk_mul_f32 v[122:123], v[114:115], s[8:9] op_sel_hi:[1,0]
	v_pk_mul_f32 v[124:125], v[116:117], s[8:9] op_sel_hi:[1,0]
	v_cndmask_b32_e64 v115, v115, v123, s[44:45]
	v_cndmask_b32_e64 v117, v117, v125, s[44:45]
	v_cndmask_b32_e64 v116, v116, v124, s[44:45]
	v_cndmask_b32_e64 v114, v114, v122, s[44:45]
	v_cndmask_b32_e64 v113, v113, v121, s[44:45]
	v_cndmask_b32_e64 v112, v112, v120, s[44:45]
	v_cndmask_b32_e64 v111, v111, v119, s[44:45]
	v_cndmask_b32_e64 v110, v110, v118, s[44:45]
	s_and_b64 vcc, exec, s[48:49]
	v_cvt_pk_bf16_f32 v118, v110, v111
	v_cvt_pk_bf16_f32 v119, v112, v113
	v_cvt_pk_bf16_f32 v120, v114, v115
	v_cvt_pk_bf16_f32 v121, v116, v117
	global_store_dwordx4 v[128:129], v[118:121], off offset:256 nt
	s_cbranch_vccnz .LBB0_181
	s_and_b64 s[22:23], s[50:51], s[52:53]
	s_xor_b64 s[22:23], s[22:23], -1
	s_and_saveexec_b64 s[50:51], s[22:23]
	s_xor_b64 s[50:51], exec, s[50:51]
	s_cbranch_execnz .LBB0_310
	s_andn2_saveexec_b64 s[50:51], s[50:51]
	s_cbranch_execnz .LBB0_311

;     __device__ __forceinline__ void operator()(const f32x4 (&acc)[2][2][4][2], const Unit& u, int wr, int wc, int fr, int fq) const {
;     ...
;                     if (is_kv) {
;                         float* dst = nullptr;
;                         if (isP && t >= 4096 - W) dst = out + okp + ((size_t)(b * W + t - (4096 - W)) * 2 + kvsel) * 256 + cit;
;                         else if (isS) dst = out + oks + ((size_t)(b * W + W - 1) * 2 + kvsel) * 256 + cit;
;                         if (dst) { *(f32x4*)dst = v0; *(f32x4*)(dst + 4) = v1; }
.LBB0_179:
	global_store_dwordx4 v[118:119], v[110:113], off nt
	global_store_dwordx4 v[118:119], v[114:117], off offset:16 nt

;     __device__ __forceinline__ void operator()(const f32x4 (&acc)[2][2][4][2], const Unit& u, int wr, int wc, int fr, int fq) const {
;     ...
;                     if (is_conv) {
;                         const int cc = pn * BM + cit - ZMQ;
;                         float* dst = nullptr;
;                         if (isP && t >= 4093) dst = out + O_CONV_P + (size_t)(b * 3 + t - 4093) * 2048 + cc;
;                         else if (isS) dst = out + O_CONV_S + (size_t)(b * 3 + 2) * 2048 + cc;
;                         if (dst) { *(f32x4*)dst = v0; *(f32x4*)(dst + 4) = v1; }
.LBB0_181:
	s_and_b64 vcc, exec, s[46:47]
	s_cbranch_vccnz .LBB0_185
	v_lshl_add_u64 v[52:53], s[96:97], 0, v[130:131]
	v_add_u32_e32 v118, s18, v158
	v_mov_b32_e32 v119, v143
	v_lshl_add_u64 v[52:53], v[118:119], 2, v[52:53]
	s_mov_b64 s[22:23], 0xfd35e00
	v_lshl_add_u64 v[118:119], v[52:53], 0, s[22:23]
	v_cmp_ne_u64_e32 vcc, 0, v[118:119]
	s_xor_b64 s[12:13], s[12:13], -1
	s_and_b64 s[22:23], s[12:13], vcc
	s_and_saveexec_b64 s[12:13], s[22:23]
	s_cbranch_execz .LBB0_184
	s_mov_b64 s[22:23], 0x200
	v_lshl_add_u64 v[52:53], v[52:53], 0, s[22:23]
	v_add_co_u32_e32 v52, vcc, 0xfd35000, v52
	global_store_dwordx4 v[118:119], v[110:113], off nt
	s_nop 0
	v_addc_co_u32_e32 v53, vcc, 0, v53, vcc
	global_store_dwordx4 v[52:53], v[114:117], off offset:3088 nt

; __device__ __forceinline__ unsigned cvt_pk_bf16(float lo, float hi) { unsigned r; asm volatile("v_cvt_pk_bf16_f32 %0, %1, %2" : "=v"(r) : "v"(lo), "v"(hi)); return r; }
;     __device__ __forceinline__ void operator()(const f32x4 (&acc)[2][2][4][2], const Unit& u, int wr, int wc, int fr, int fq) const {
;     ...
;                     f32x4 v0 = acc[ai][bj][m][0], v1 = acc[ai][bj][m][1];
;                     const int cit = bj * HALF + wc * 32 + fq * 8;
;                     if (do_rope) {
; #pragma unroll
;                         for (int j = 0; j < 4; ++j) {
;                             const float p0 = __shfl_xor(v0[j], 16), p1 = __shfl_xor(v1[j], 16);
;                             const float r0 = v0[j] * cosv[j] + sgn * p0 * sinv[j], r1 = v1[j] * cosv[4 + j] + sgn * p1 * sinv[4 + j];
;                             v0[j] = fq < 2 ? r0 : v0[j]; v1[j] = fq < 2 ? r1 : v1[j];
;                         }
;                     }
;                     if (pn < 3) { v0 = v0 * QSCALE; v1 = v1 * QSCALE; }
;                     u32x4 w; w.x = cvt_pk_bf16(v0[0], v0[1]); w.y = cvt_pk_bf16(v0[2], v0[3]); w.z = cvt_pk_bf16(v1[0], v1[1]); w.w = cvt_pk_bf16(v1[2], v1[3]);
;                     *(u32x4*)(Z + (size_t)row * NZ + pn * BM + cit) = w;
;                     if (is_kv) {
;                         float* dst = nullptr;
;                         if (isP && t >= 4096 - W) dst = out + okp + ((size_t)(b * W + t - (4096 - W)) * 2 + kvsel) * 256 + cit;
;                         else if (isS) dst = out + oks + ((size_t)(b * W + W - 1) * 2 + kvsel) * 256 + cit;
;                         if (dst) { *(f32x4*)dst = v0; *(f32x4*)(dst + 4) = v1; }
.LBB0_189:
	v_pk_mul_f32 v[116:117], v[102:103], s[8:9] op_sel_hi:[1,0]
	v_cmp_le_u32_e64 s[52:53], s29, v52
	v_cndmask_b32_e64 v103, v103, v117, s[44:45]
	v_cndmask_b32_e64 v102, v102, v116, s[44:45]
	v_mov_b64_e32 v[116:117], s[2:3]
	v_add_u32_e32 v52, s10, v52
	v_mad_i64_i32 v[110:111], s[12:13], v110, s9, v[116:117]
	v_ashrrev_i32_e32 v53, 31, v52
	v_pk_mul_f32 v[112:113], v[106:107], s[8:9] op_sel_hi:[1,0]
	v_pk_mul_f32 v[114:115], v[108:109], s[8:9] op_sel_hi:[1,0]
	v_pk_mul_f32 v[118:119], v[104:105], s[8:9] op_sel_hi:[1,0]
	v_lshl_add_u64 v[110:111], s[18:19], 1, v[110:111]
	v_lshlrev_b64 v[52:53], 11, v[52:53]
	v_cndmask_b32_e64 v105, v105, v119, s[44:45]
	v_cndmask_b32_e64 v104, v104, v118, s[44:45]
	v_cndmask_b32_e64 v109, v109, v115, s[44:45]
	v_cndmask_b32_e64 v108, v108, v114, s[44:45]
	v_cndmask_b32_e64 v107, v107, v113, s[44:45]
	v_cndmask_b32_e64 v106, v106, v112, s[44:45]
	v_lshl_add_u64 v[110:111], v[110:111], 0, v[142:143]
	s_and_b64 vcc, exec, s[48:49]
	v_cvt_pk_bf16_f32 v112, v106, v107
	v_cvt_pk_bf16_f32 v113, v108, v109
	v_cvt_pk_bf16_f32 v114, v102, v103
	v_cvt_pk_bf16_f32 v115, v104, v105
	global_store_dwordx4 v[110:111], v[112:115], off nt
	s_cbranch_vccnz .LBB0_193
	s_and_b64 s[12:13], s[50:51], s[52:53]
	s_lshl_b32 s11, s27, 2
	s_add_u32 s22, s96, s11
	s_addc_u32 s23, s97, 0
	v_lshl_add_u64 v[112:113], s[22:23], 0, v[52:53]
	v_lshl_add_u64 v[112:113], v[112:113], 0, s[4:5]
	v_cmp_ne_u64_e32 vcc, 0, v[112:113]
	s_and_b64 s[22:23], s[12:13], vcc
	s_and_saveexec_b64 s[12:13], s[22:23]
	s_cbranch_execz .LBB0_192
	v_lshlrev_b32_e32 v114, 2, v158
	v_mov_b32_e32 v115, v143
	v_lshl_add_u64 v[112:113], v[112:113], 0, v[114:115]
	global_store_dwordx4 v[112:113], v[106:109], off nt
	global_store_dwordx4 v[112:113], v[102:105], off offset:16 nt

; __device__ __forceinline__ unsigned cvt_pk_bf16(float lo, float hi) { unsigned r; asm volatile("v_cvt_pk_bf16_f32 %0, %1, %2" : "=v"(r) : "v"(lo), "v"(hi)); return r; }
;     __device__ __forceinline__ void operator()(const f32x4 (&acc)[2][2][4][2], const Unit& u, int wr, int wc, int fr, int fq) const {
;     ...
;                     if (pn < 3) { v0 = v0 * QSCALE; v1 = v1 * QSCALE; }
;                     u32x4 w; w.x = cvt_pk_bf16(v0[0], v0[1]); w.y = cvt_pk_bf16(v0[2], v0[3]); w.z = cvt_pk_bf16(v1[0], v1[1]); w.w = cvt_pk_bf16(v1[2], v1[3]);
;                     *(u32x4*)(Z + (size_t)row * NZ + pn * BM + cit) = w;
;                     if (is_kv) {
;                         float* dst = nullptr;
;                         if (isP && t >= 4096 - W) dst = out + okp + ((size_t)(b * W + t - (4096 - W)) * 2 + kvsel) * 256 + cit;
;                         else if (isS) dst = out + oks + ((size_t)(b * W + W - 1) * 2 + kvsel) * 256 + cit;
;                         if (dst) { *(f32x4*)dst = v0; *(f32x4*)(dst + 4) = v1; }
.LBB0_195:
	v_pk_mul_f32 v[102:103], v[98:99], s[8:9] op_sel_hi:[1,0]
	v_pk_mul_f32 v[104:105], v[100:101], s[8:9] op_sel_hi:[1,0]
	v_pk_mul_f32 v[106:107], v[94:95], s[8:9] op_sel_hi:[1,0]
	v_pk_mul_f32 v[108:109], v[96:97], s[8:9] op_sel_hi:[1,0]
	s_and_b64 s[12:13], s[92:93], s[50:51]
	v_cndmask_b32_e64 v97, v97, v109, s[44:45]
	v_cndmask_b32_e64 v96, v96, v108, s[44:45]
	v_cndmask_b32_e64 v95, v95, v107, s[44:45]
	v_cndmask_b32_e64 v94, v94, v106, s[44:45]
	v_cndmask_b32_e64 v101, v101, v105, s[44:45]
	v_cndmask_b32_e64 v100, v100, v104, s[44:45]
	v_cndmask_b32_e64 v99, v99, v103, s[44:45]
	v_cndmask_b32_e64 v98, v98, v102, s[44:45]
	s_and_b64 s[22:23], s[12:13], s[52:53]
	v_cvt_pk_bf16_f32 v102, v98, v99
	v_cvt_pk_bf16_f32 v103, v100, v101
	v_cvt_pk_bf16_f32 v104, v94, v95
	v_cvt_pk_bf16_f32 v105, v96, v97
	global_store_dwordx4 v[110:111], v[102:105], off offset:256 nt
	s_and_saveexec_b64 s[12:13], s[22:23]
	s_cbranch_execz .LBB0_197
	s_lshl_b32 s11, s27, 2
	s_add_u32 s22, s96, s11
	s_addc_u32 s23, s97, 0
	v_lshl_add_u64 v[52:53], s[22:23], 0, v[52:53]
	v_lshl_add_u64 v[52:53], v[52:53], 0, s[4:5]
	v_lshlrev_b32_e32 v102, 2, v158
	v_mov_b32_e32 v103, v143
	v_lshl_add_u64 v[52:53], v[52:53], 0, v[102:103]
	global_store_dwordx4 v[52:53], v[98:101], off offset:512 nt
	global_store_dwordx4 v[52:53], v[94:97], off offset:528 nt

; __device__ __forceinline__ unsigned cvt_pk_bf16(float lo, float hi) { unsigned r; asm volatile("v_cvt_pk_bf16_f32 %0, %1, %2" : "=v"(r) : "v"(lo), "v"(hi)); return r; }
;     __device__ __forceinline__ void operator()(const f32x4 (&acc)[2][2][4][2], const Unit& u, int wr, int wc, int fr, int fq) const {
;     ...
;                     f32x4 v0 = acc[ai][bj][m][0], v1 = acc[ai][bj][m][1];
;                     const int cit = bj * HALF + wc * 32 + fq * 8;
;                     if (do_rope) {
; #pragma unroll
;                         for (int j = 0; j < 4; ++j) {
;                             const float p0 = __shfl_xor(v0[j], 16), p1 = __shfl_xor(v1[j], 16);
;                             const float r0 = v0[j] * cosv[j] + sgn * p0 * sinv[j], r1 = v1[j] * cosv[4 + j] + sgn * p1 * sinv[4 + j];
;                             v0[j] = fq < 2 ? r0 : v0[j]; v1[j] = fq < 2 ? r1 : v1[j];
;                         }
;                     }
;                     if (pn < 3) { v0 = v0 * QSCALE; v1 = v1 * QSCALE; }
;                     u32x4 w; w.x = cvt_pk_bf16(v0[0], v0[1]); w.y = cvt_pk_bf16(v0[2], v0[3]); w.z = cvt_pk_bf16(v1[0], v1[1]); w.w = cvt_pk_bf16(v1[2], v1[3]);
;                     *(u32x4*)(Z + (size_t)row * NZ + pn * BM + cit) = w;
;                     if (is_kv) {
;                         float* dst = nullptr;
;                         if (isP && t >= 4096 - W) dst = out + okp + ((size_t)(b * W + t - (4096 - W)) * 2 + kvsel) * 256 + cit;
;                         else if (isS) dst = out + oks + ((size_t)(b * W + W - 1) * 2 + kvsel) * 256 + cit;
;                         if (dst) { *(f32x4*)dst = v0; *(f32x4*)(dst + 4) = v1; }
.LBB0_201:
	v_pk_mul_f32 v[96:97], v[86:87], s[8:9] op_sel_hi:[1,0]
	v_add_u32_e32 v52, s10, v98
	v_cndmask_b32_e64 v87, v87, v97, s[44:45]
	v_cndmask_b32_e64 v86, v86, v96, s[44:45]
	v_mov_b64_e32 v[96:97], s[2:3]
	v_mad_i64_i32 v[94:95], s[10:11], v94, s9, v[96:97]
	v_ashrrev_i32_e32 v53, 31, v52
	v_pk_mul_f32 v[100:101], v[88:89], s[8:9] op_sel_hi:[1,0]
	v_pk_mul_f32 v[102:103], v[90:91], s[8:9] op_sel_hi:[1,0]
	v_pk_mul_f32 v[104:105], v[92:93], s[8:9] op_sel_hi:[1,0]
	v_lshl_add_u64 v[94:95], s[18:19], 1, v[94:95]
	v_cmp_le_u32_e64 s[52:53], s29, v98
	v_lshlrev_b64 v[52:53], 11, v[52:53]
	v_cndmask_b32_e64 v93, v93, v105, s[44:45]
	v_cndmask_b32_e64 v92, v92, v104, s[44:45]
	v_cndmask_b32_e64 v91, v91, v103, s[44:45]
	v_cndmask_b32_e64 v90, v90, v102, s[44:45]
	v_cndmask_b32_e64 v89, v89, v101, s[44:45]
	v_cndmask_b32_e64 v88, v88, v100, s[44:45]
	v_lshl_add_u64 v[94:95], v[94:95], 0, v[142:143]
	s_and_b64 vcc, exec, s[48:49]
	v_cvt_pk_bf16_f32 v100, v86, v87
	v_cvt_pk_bf16_f32 v101, v88, v89
	v_cvt_pk_bf16_f32 v102, v90, v91
	v_cvt_pk_bf16_f32 v103, v92, v93
	global_store_dwordx4 v[94:95], v[100:103], off nt
	s_cbranch_vccnz .LBB0_205
	s_and_b64 s[10:11], s[50:51], s[52:53]
	s_lshl_b32 s12, s27, 2
	s_add_u32 s12, s96, s12
	s_addc_u32 s13, s97, 0
	v_lshl_add_u64 v[96:97], s[12:13], 0, v[52:53]
	v_lshl_add_u64 v[96:97], v[96:97], 0, s[4:5]
	v_cmp_ne_u64_e32 vcc, 0, v[96:97]
	s_and_b64 s[10:11], s[10:11], vcc
	s_and_saveexec_b64 s[12:13], s[10:11]
	s_cbranch_execz .LBB0_204
	v_lshlrev_b32_e32 v100, 2, v158
	v_mov_b32_e32 v101, v143
	v_lshl_add_u64 v[96:97], v[96:97], 0, v[100:101]
	global_store_dwordx4 v[96:97], v[86:89], off nt
	global_store_dwordx4 v[96:97], v[90:93], off offset:16 nt

;     __device__ __forceinline__ void operator()(const f32x4 (&acc)[2][2][4][2], const Unit& u, int wr, int wc, int fr, int fq) const {
;     ...
;                     if (is_conv) {
;                         const int cc = pn * BM + cit - ZMQ;
;                         float* dst = nullptr;
;                         if (isP && t >= 4093) dst = out + O_CONV_P + (size_t)(b * 3 + t - 4093) * 2048 + cc;
;                         else if (isS) dst = out + O_CONV_S + (size_t)(b * 3 + 2) * 2048 + cc;
;                         if (dst) { *(f32x4*)dst = v0; *(f32x4*)(dst + 4) = v1; }
.LBB0_205:
	s_mul_i32 s1, s1, 3
	s_addk_i32 s1, 0xf003
	s_movk_i32 s10, 0xffc
	v_add_u32_e32 v96, s1, v98
	v_cmp_lt_u32_e32 vcc, s10, v98
	v_ashrrev_i32_e32 v97, 31, v96
	s_and_b64 s[12:13], s[50:51], vcc
	s_and_b64 vcc, exec, s[46:47]
	v_lshlrev_b64 v[96:97], 13, v[96:97]
	s_cbranch_vccnz .LBB0_209
	v_or_b32_e32 v98, s18, v158
	v_mov_b32_e32 v99, v143
	v_lshl_add_u64 v[100:101], s[96:97], 0, v[96:97]
	v_lshl_add_u64 v[98:99], v[98:99], 2, v[100:101]
	s_mov_b64 s[10:11], 0xfd1dc00
	v_lshl_add_u64 v[100:101], v[98:99], 0, s[10:11]
	v_cmp_ne_u64_e32 vcc, 0, v[100:101]
	s_and_b64 s[10:11], s[12:13], vcc
	s_and_saveexec_b64 s[22:23], s[10:11]
	s_cbranch_execz .LBB0_208
	global_store_dwordx4 v[100:101], v[86:89], off nt
	s_nop 1
	v_add_co_u32_e32 v86, vcc, 0xfd1d000, v98
	s_nop 1
	v_addc_co_u32_e32 v87, vcc, 0, v99, vcc
	global_store_dwordx4 v[86:87], v[90:93], off offset:3088 nt

; __device__ __forceinline__ unsigned cvt_pk_bf16(float lo, float hi) { unsigned r; asm volatile("v_cvt_pk_bf16_f32 %0, %1, %2" : "=v"(r) : "v"(lo), "v"(hi)); return r; }
;     __device__ __forceinline__ void operator()(const f32x4 (&acc)[2][2][4][2], const Unit& u, int wr, int wc, int fr, int fq) const {
;     ...
;                     if (pn < 3) { v0 = v0 * QSCALE; v1 = v1 * QSCALE; }
;                     u32x4 w; w.x = cvt_pk_bf16(v0[0], v0[1]); w.y = cvt_pk_bf16(v0[2], v0[3]); w.z = cvt_pk_bf16(v1[0], v1[1]); w.w = cvt_pk_bf16(v1[2], v1[3]);
;                     *(u32x4*)(Z + (size_t)row * NZ + pn * BM + cit) = w;
;                     if (is_kv) {
;                         float* dst = nullptr;
;                         if (isP && t >= 4096 - W) dst = out + okp + ((size_t)(b * W + t - (4096 - W)) * 2 + kvsel) * 256 + cit;
;                         else if (isS) dst = out + oks + ((size_t)(b * W + W - 1) * 2 + kvsel) * 256 + cit;
;                         if (dst) { *(f32x4*)dst = v0; *(f32x4*)(dst + 4) = v1; }
;                     }
;                     if (is_conv) {
;                         const int cc = pn * BM + cit - ZMQ;
;                         float* dst = nullptr;
;                         if (isP && t >= 4093) dst = out + O_CONV_P + (size_t)(b * 3 + t - 4093) * 2048 + cc;
;                         else if (isS) dst = out + O_CONV_S + (size_t)(b * 3 + 2) * 2048 + cc;
;                         if (dst) { *(f32x4*)dst = v0; *(f32x4*)(dst + 4) = v1; }
.LBB0_211:
	v_pk_mul_f32 v[86:87], v[78:79], s[8:9] op_sel_hi:[1,0]
	v_pk_mul_f32 v[88:89], v[80:81], s[8:9] op_sel_hi:[1,0]
	v_pk_mul_f32 v[90:91], v[82:83], s[8:9] op_sel_hi:[1,0]
	v_pk_mul_f32 v[92:93], v[84:85], s[8:9] op_sel_hi:[1,0]
	s_and_b64 s[10:11], s[92:93], s[50:51]
	v_cndmask_b32_e64 v85, v85, v93, s[44:45]
	v_cndmask_b32_e64 v84, v84, v92, s[44:45]
	v_cndmask_b32_e64 v83, v83, v91, s[44:45]
	v_cndmask_b32_e64 v82, v82, v90, s[44:45]
	v_cndmask_b32_e64 v81, v81, v89, s[44:45]
	v_cndmask_b32_e64 v80, v80, v88, s[44:45]
	v_cndmask_b32_e64 v79, v79, v87, s[44:45]
	v_cndmask_b32_e64 v78, v78, v86, s[44:45]
	s_and_b64 s[10:11], s[10:11], s[52:53]
	v_cvt_pk_bf16_f32 v86, v78, v79
	v_cvt_pk_bf16_f32 v87, v80, v81
	v_cvt_pk_bf16_f32 v88, v82, v83
	v_cvt_pk_bf16_f32 v89, v84, v85
	global_store_dwordx4 v[94:95], v[86:89], off offset:256 nt
	s_and_saveexec_b64 s[50:51], s[10:11]
	s_cbranch_execz .LBB0_213
	s_lshl_b32 s1, s27, 2
	s_add_u32 s10, s96, s1
	s_addc_u32 s11, s97, 0
	v_lshl_add_u64 v[52:53], s[10:11], 0, v[52:53]
	v_lshl_add_u64 v[52:53], v[52:53], 0, s[4:5]
	v_lshlrev_b32_e32 v86, 2, v158
	v_mov_b32_e32 v87, v143
	v_lshl_add_u64 v[52:53], v[52:53], 0, v[86:87]
	global_store_dwordx4 v[52:53], v[78:81], off offset:512 nt
	global_store_dwordx4 v[52:53], v[82:85], off offset:528 nt
.LBB0_213:
	s_or_b64 exec, exec, s[50:51]
	s_and_b64 vcc, exec, s[46:47]
	s_cbranch_vccnz .LBB0_217
	v_lshl_add_u64 v[52:53], s[96:97], 0, v[96:97]
	v_add_u32_e32 v86, s18, v158
	v_mov_b32_e32 v87, v143
	v_lshl_add_u64 v[52:53], v[86:87], 2, v[52:53]
	s_mov_b64 s[10:11], 0xfd1de00
	v_lshl_add_u64 v[86:87], v[52:53], 0, s[10:11]
	v_cmp_ne_u64_e32 vcc, 0, v[86:87]
	s_and_b64 s[10:11], s[12:13], vcc
	s_and_saveexec_b64 s[12:13], s[10:11]
	s_cbranch_execz .LBB0_216
	s_mov_b64 s[10:11], 0x200
	v_lshl_add_u64 v[52:53], v[52:53], 0, s[10:11]
	v_add_co_u32_e32 v52, vcc, 0xfd1d000, v52
	global_store_dwordx4 v[86:87], v[78:81], off nt
	s_nop 0
	v_addc_co_u32_e32 v53, vcc, 0, v53, vcc
	global_store_dwordx4 v[52:53], v[82:85], off offset:3088 nt

; __device__ __forceinline__ unsigned cvt_pk_bf16(float lo, float hi) { unsigned r; asm volatile("v_cvt_pk_bf16_f32 %0, %1, %2" : "=v"(r) : "v"(lo), "v"(hi)); return r; }
;     __device__ __forceinline__ void operator()(const f32x4 (&acc)[2][2][4][2], const Unit& u, int wr, int wc, int fr, int fq) const {
;     ...
;                 const int row = u.pm * BM + ai * HALF + wr * 64 + m * 16 + fr;
;                 const bool isP = row < MP, isS = (row >= MP) && (row < MT);
;                 const int b = isP ? (row >> 12) : (row - MP);
;                 const int t = row & 4095;
;                 float cosv[8], sinv[8];
;                 if (do_rope) {
;                     const f32x4* cs = (const f32x4*)(rope + (size_t)(isP ? t : 4096) * 16);
; #pragma unroll
;                     for (int q = 0; q < 4; ++q) { const f32x4 c = cs[q]; cosv[2 * q] = c[0]; sinv[2 * q] = c[1]; cosv[2 * q + 1] = c[2]; sinv[2 * q + 1] = c[3]; }
;                 }
; #pragma unroll
;                 for (int bj = 0; bj < 2; ++bj) {
;                     f32x4 v0 = acc[ai][bj][m][0], v1 = acc[ai][bj][m][1];
;                     const int cit = bj * HALF + wc * 32 + fq * 8;
;                     if (do_rope) {
; #pragma unroll
;                         for (int j = 0; j < 4; ++j) {
;                             const float p0 = __shfl_xor(v0[j], 16), p1 = __shfl_xor(v1[j], 16);
;                             const float r0 = v0[j] * cosv[j] + sgn * p0 * sinv[j], r1 = v1[j] * cosv[4 + j] + sgn * p1 * sinv[4 + j];
;                             v0[j] = fq < 2 ? r0 : v0[j]; v1[j] = fq < 2 ? r1 : v1[j];
;                         }
;                     }
;                     if (pn < 3) { v0 = v0 * QSCALE; v1 = v1 * QSCALE; }
;                     u32x4 w; w.x = cvt_pk_bf16(v0[0], v0[1]); w.y = cvt_pk_bf16(v0[2], v0[3]); w.z = cvt_pk_bf16(v1[0], v1[1]); w.w = cvt_pk_bf16(v1[2], v1[3]);
;                     *(u32x4*)(Z + (size_t)row * NZ + pn * BM + cit) = w;
.LBB0_221:
	s_ashr_i32 s1, s14, 12
	v_add_u32_e32 v53, 0xffffc000, v88
	v_mov_b32_e32 v78, s1
	v_cndmask_b32_e64 v84, v53, v78, s[50:51]
	s_lshl_b32 s10, s1, s56
	v_pk_mul_f32 v[80:81], v[70:71], s[8:9] op_sel_hi:[1,0]
	s_add_i32 s10, s10, s15
	v_lshlrev_b32_e32 v78, s56, v84
	v_cndmask_b32_e64 v71, v71, v81, s[44:45]
	v_cndmask_b32_e64 v70, v70, v80, s[44:45]
	v_mov_b64_e32 v[80:81], s[2:3]
	v_cmp_le_u32_e64 s[52:53], s29, v52
	v_add_u32_e32 v52, s10, v52
	v_add_u32_e32 v78, s57, v78
	s_cmpk_lg_i32 s14, 0x4000
	v_mad_i64_i32 v[80:81], s[14:15], v88, s9, v[80:81]
	v_ashrrev_i32_e32 v53, 31, v52
	v_ashrrev_i32_e32 v79, 31, v78
	v_pk_mul_f32 v[82:83], v[72:73], s[8:9] op_sel_hi:[1,0]
	v_pk_mul_f32 v[86:87], v[74:75], s[8:9] op_sel_hi:[1,0]
	v_pk_mul_f32 v[90:91], v[76:77], s[8:9] op_sel_hi:[1,0]
	v_lshl_add_u64 v[80:81], s[18:19], 1, v[80:81]
	v_lshlrev_b64 v[52:53], 11, v[52:53]
	v_lshlrev_b64 v[78:79], 11, v[78:79]
	s_cselect_b64 s[12:13], -1, 0
	v_cndmask_b32_e64 v77, v77, v91, s[44:45]
	v_cndmask_b32_e64 v76, v76, v90, s[44:45]
	v_cndmask_b32_e64 v75, v75, v87, s[44:45]
	v_cndmask_b32_e64 v74, v74, v86, s[44:45]
	v_cndmask_b32_e64 v73, v73, v83, s[44:45]
	v_cndmask_b32_e64 v72, v72, v82, s[44:45]
	v_lshl_add_u64 v[80:81], v[80:81], 0, v[142:143]
	s_and_b64 vcc, exec, s[48:49]
	v_cvt_pk_bf16_f32 v90, v70, v71
	v_cvt_pk_bf16_f32 v91, v72, v73
	v_cvt_pk_bf16_f32 v92, v74, v75
	v_cvt_pk_bf16_f32 v93, v76, v77
	global_store_dwordx4 v[80:81], v[90:93], off nt
	s_cbranch_vccnz .LBB0_227
	s_and_b64 s[14:15], s[50:51], s[52:53]
	s_xor_b64 s[14:15], s[14:15], -1
	s_and_saveexec_b64 s[22:23], s[14:15]
	s_xor_b64 vcc, exec, s[22:23]
	s_cbranch_execnz .LBB0_312
	s_andn2_saveexec_b64 vcc, vcc
	s_cbranch_execnz .LBB0_313

;     __device__ __forceinline__ void operator()(const f32x4 (&acc)[2][2][4][2], const Unit& u, int wr, int wc, int fr, int fq) const {
;     ...
;                     if (is_kv) {
;                         float* dst = nullptr;
;                         if (isP && t >= 4096 - W) dst = out + okp + ((size_t)(b * W + t - (4096 - W)) * 2 + kvsel) * 256 + cit;
;                         else if (isS) dst = out + oks + ((size_t)(b * W + W - 1) * 2 + kvsel) * 256 + cit;
;                         if (dst) { *(f32x4*)dst = v0; *(f32x4*)(dst + 4) = v1; }
.LBB0_225:
	global_store_dwordx4 v[82:83], v[70:73], off nt
	global_store_dwordx4 v[82:83], v[74:77], off offset:16 nt

;     __device__ __forceinline__ void operator()(const f32x4 (&acc)[2][2][4][2], const Unit& u, int wr, int wc, int fr, int fq) const {
;     ...
;                     if (is_conv) {
;                         const int cc = pn * BM + cit - ZMQ;
;                         float* dst = nullptr;
;                         if (isP && t >= 4093) dst = out + O_CONV_P + (size_t)(b * 3 + t - 4093) * 2048 + cc;
;                         else if (isS) dst = out + O_CONV_S + (size_t)(b * 3 + 2) * 2048 + cc;
;                         if (dst) { *(f32x4*)dst = v0; *(f32x4*)(dst + 4) = v1; }
.LBB0_227:
	v_lshl_add_u32 v82, v84, 1, v84
	v_ashrrev_i32_e32 v83, 31, v82
	v_lshlrev_b64 v[82:83], 13, v[82:83]
	s_mov_b64 s[14:15], 0x4000
	s_and_b64 vcc, exec, s[46:47]
	v_lshl_add_u64 v[82:83], v[82:83], 0, s[14:15]
	s_cbranch_vccnz .LBB0_231
	v_or_b32_e32 v84, s18, v158
	v_lshl_add_u64 v[86:87], s[96:97], 0, v[82:83]
	v_mov_b32_e32 v85, v143
	v_lshl_add_u64 v[84:85], v[84:85], 2, v[86:87]
	s_mov_b64 s[14:15], 0xfd35c00
	v_lshl_add_u64 v[86:87], v[84:85], 0, s[14:15]
	v_cmp_ne_u64_e32 vcc, 0, v[86:87]
	s_xor_b64 s[14:15], s[12:13], -1
	s_and_b64 s[14:15], s[14:15], vcc
	s_and_saveexec_b64 s[22:23], s[14:15]
	s_cbranch_execz .LBB0_230
	global_store_dwordx4 v[86:87], v[70:73], off nt
	s_nop 1
	v_add_co_u32_e32 v70, vcc, 0xfd35000, v84
	s_nop 1
	v_addc_co_u32_e32 v71, vcc, 0, v85, vcc
	global_store_dwordx4 v[70:71], v[74:77], off offset:3088 nt

; __device__ __forceinline__ unsigned cvt_pk_bf16(float lo, float hi) { unsigned r; asm volatile("v_cvt_pk_bf16_f32 %0, %1, %2" : "=v"(r) : "v"(lo), "v"(hi)); return r; }
;     __device__ __forceinline__ void operator()(const f32x4 (&acc)[2][2][4][2], const Unit& u, int wr, int wc, int fr, int fq) const {
;     ...
;                     f32x4 v0 = acc[ai][bj][m][0], v1 = acc[ai][bj][m][1];
;                     const int cit = bj * HALF + wc * 32 + fq * 8;
;                     if (do_rope) {
; #pragma unroll
;                         for (int j = 0; j < 4; ++j) {
;                             const float p0 = __shfl_xor(v0[j], 16), p1 = __shfl_xor(v1[j], 16);
;                             const float r0 = v0[j] * cosv[j] + sgn * p0 * sinv[j], r1 = v1[j] * cosv[4 + j] + sgn * p1 * sinv[4 + j];
;                             v0[j] = fq < 2 ? r0 : v0[j]; v1[j] = fq < 2 ? r1 : v1[j];
;                         }
;                     }
;                     if (pn < 3) { v0 = v0 * QSCALE; v1 = v1 * QSCALE; }
;                     u32x4 w; w.x = cvt_pk_bf16(v0[0], v0[1]); w.y = cvt_pk_bf16(v0[2], v0[3]); w.z = cvt_pk_bf16(v1[0], v1[1]); w.w = cvt_pk_bf16(v1[2], v1[3]);
;                     *(u32x4*)(Z + (size_t)row * NZ + pn * BM + cit) = w;
.LBB0_233:
	v_pk_mul_f32 v[70:71], v[62:63], s[8:9] op_sel_hi:[1,0]
	v_pk_mul_f32 v[72:73], v[64:65], s[8:9] op_sel_hi:[1,0]
	v_pk_mul_f32 v[74:75], v[66:67], s[8:9] op_sel_hi:[1,0]
	v_pk_mul_f32 v[76:77], v[68:69], s[8:9] op_sel_hi:[1,0]
	v_cndmask_b32_e64 v67, v67, v75, s[44:45]
	v_cndmask_b32_e64 v69, v69, v77, s[44:45]
	v_cndmask_b32_e64 v68, v68, v76, s[44:45]
	v_cndmask_b32_e64 v66, v66, v74, s[44:45]
	v_cndmask_b32_e64 v65, v65, v73, s[44:45]
	v_cndmask_b32_e64 v64, v64, v72, s[44:45]
	v_cndmask_b32_e64 v63, v63, v71, s[44:45]
	v_cndmask_b32_e64 v62, v62, v70, s[44:45]
	s_and_b64 vcc, exec, s[48:49]
	v_cvt_pk_bf16_f32 v70, v62, v63
	v_cvt_pk_bf16_f32 v71, v64, v65
	v_cvt_pk_bf16_f32 v72, v66, v67
	v_cvt_pk_bf16_f32 v73, v68, v69
	global_store_dwordx4 v[80:81], v[70:73], off offset:256 nt
	s_cbranch_vccnz .LBB0_239
	s_and_b64 s[14:15], s[50:51], s[52:53]
	s_xor_b64 s[14:15], s[14:15], -1
	s_and_saveexec_b64 s[22:23], s[14:15]
	s_xor_b64 s[50:51], exec, s[22:23]
	s_cbranch_execnz .LBB0_314
	s_andn2_saveexec_b64 s[50:51], s[50:51]
	s_cbranch_execnz .LBB0_315

;     __device__ __forceinline__ void operator()(const f32x4 (&acc)[2][2][4][2], const Unit& u, int wr, int wc, int fr, int fq) const {
;     ...
;                     if (is_kv) {
;                         float* dst = nullptr;
;                         if (isP && t >= 4096 - W) dst = out + okp + ((size_t)(b * W + t - (4096 - W)) * 2 + kvsel) * 256 + cit;
;                         else if (isS) dst = out + oks + ((size_t)(b * W + W - 1) * 2 + kvsel) * 256 + cit;
;                         if (dst) { *(f32x4*)dst = v0; *(f32x4*)(dst + 4) = v1; }
.LBB0_237:
	global_store_dwordx4 v[70:71], v[62:65], off nt
	global_store_dwordx4 v[70:71], v[66:69], off offset:16 nt

;     __device__ __forceinline__ void operator()(const f32x4 (&acc)[2][2][4][2], const Unit& u, int wr, int wc, int fr, int fq) const {
;     ...
;                     if (is_conv) {
;                         const int cc = pn * BM + cit - ZMQ;
;                         float* dst = nullptr;
;                         if (isP && t >= 4093) dst = out + O_CONV_P + (size_t)(b * 3 + t - 4093) * 2048 + cc;
;                         else if (isS) dst = out + O_CONV_S + (size_t)(b * 3 + 2) * 2048 + cc;
;                         if (dst) { *(f32x4*)dst = v0; *(f32x4*)(dst + 4) = v1; }
.LBB0_239:
	s_and_b64 vcc, exec, s[46:47]
	s_cbranch_vccnz .LBB0_243
	v_lshl_add_u64 v[52:53], s[96:97], 0, v[82:83]
	v_add_u32_e32 v70, s18, v158
	v_mov_b32_e32 v71, v143
	v_lshl_add_u64 v[52:53], v[70:71], 2, v[52:53]
	s_mov_b64 s[14:15], 0xfd35e00
	v_lshl_add_u64 v[70:71], v[52:53], 0, s[14:15]
	v_cmp_ne_u64_e32 vcc, 0, v[70:71]
	s_xor_b64 s[14:15], s[12:13], -1
	s_and_b64 s[14:15], s[14:15], vcc
	s_and_saveexec_b64 s[22:23], s[14:15]
	s_cbranch_execz .LBB0_242
	s_mov_b64 s[14:15], 0x200
	v_lshl_add_u64 v[52:53], v[52:53], 0, s[14:15]
	v_add_co_u32_e32 v52, vcc, 0xfd35000, v52
	global_store_dwordx4 v[70:71], v[62:65], off nt
	s_nop 0
	v_addc_co_u32_e32 v53, vcc, 0, v53, vcc
	global_store_dwordx4 v[52:53], v[66:69], off offset:3088 nt

; __device__ __forceinline__ unsigned cvt_pk_bf16(float lo, float hi) { unsigned r; asm volatile("v_cvt_pk_bf16_f32 %0, %1, %2" : "=v"(r) : "v"(lo), "v"(hi)); return r; }
;     __device__ __forceinline__ void operator()(const f32x4 (&acc)[2][2][4][2], const Unit& u, int wr, int wc, int fr, int fq) const {
;     ...
;                 const int row = u.pm * BM + ai * HALF + wr * 64 + m * 16 + fr;
;                 const bool isP = row < MP, isS = (row >= MP) && (row < MT);
;                 const int b = isP ? (row >> 12) : (row - MP);
;                 const int t = row & 4095;
;                 float cosv[8], sinv[8];
;                 if (do_rope) {
;                     const f32x4* cs = (const f32x4*)(rope + (size_t)(isP ? t : 4096) * 16);
; #pragma unroll
;                     for (int q = 0; q < 4; ++q) { const f32x4 c = cs[q]; cosv[2 * q] = c[0]; sinv[2 * q] = c[1]; cosv[2 * q + 1] = c[2]; sinv[2 * q + 1] = c[3]; }
;                 }
; #pragma unroll
;                 for (int bj = 0; bj < 2; ++bj) {
;                     f32x4 v0 = acc[ai][bj][m][0], v1 = acc[ai][bj][m][1];
;                     const int cit = bj * HALF + wc * 32 + fq * 8;
;                     if (do_rope) {
; #pragma unroll
;                         for (int j = 0; j < 4; ++j) {
;                             const float p0 = __shfl_xor(v0[j], 16), p1 = __shfl_xor(v1[j], 16);
;                             const float r0 = v0[j] * cosv[j] + sgn * p0 * sinv[j], r1 = v1[j] * cosv[4 + j] + sgn * p1 * sinv[4 + j];
;                             v0[j] = fq < 2 ? r0 : v0[j]; v1[j] = fq < 2 ? r1 : v1[j];
;                         }
;                     }
;                     if (pn < 3) { v0 = v0 * QSCALE; v1 = v1 * QSCALE; }
;                     u32x4 w; w.x = cvt_pk_bf16(v0[0], v0[1]); w.y = cvt_pk_bf16(v0[2], v0[3]); w.z = cvt_pk_bf16(v1[0], v1[1]); w.w = cvt_pk_bf16(v1[2], v1[3]);
;                     *(u32x4*)(Z + (size_t)row * NZ + pn * BM + cit) = w;
.LBB0_247:
	v_add_u32_e32 v53, 0xffffc010, v88
	v_mov_b32_e32 v62, s1
	v_cndmask_b32_e64 v68, v53, v62, s[50:51]
	v_pk_mul_f32 v[66:67], v[54:55], s[8:9] op_sel_hi:[1,0]
	v_lshlrev_b32_e32 v62, s56, v68
	v_cndmask_b32_e64 v55, v55, v67, s[44:45]
	v_cndmask_b32_e64 v54, v54, v66, s[44:45]
	v_mov_b64_e32 v[66:67], s[2:3]
	v_cmp_le_u32_e64 s[52:53], s29, v52
	v_add_u32_e32 v52, s10, v52
	v_add_u32_e32 v62, s57, v62
	v_mad_i64_i32 v[64:65], s[14:15], v64, s9, v[66:67]
	v_ashrrev_i32_e32 v53, 31, v52
	v_ashrrev_i32_e32 v63, 31, v62
	v_pk_mul_f32 v[70:71], v[56:57], s[8:9] op_sel_hi:[1,0]
	v_pk_mul_f32 v[72:73], v[58:59], s[8:9] op_sel_hi:[1,0]
	v_pk_mul_f32 v[74:75], v[60:61], s[8:9] op_sel_hi:[1,0]
	v_lshl_add_u64 v[64:65], s[18:19], 1, v[64:65]
	v_lshlrev_b64 v[52:53], 11, v[52:53]
	v_lshlrev_b64 v[62:63], 11, v[62:63]
	v_cndmask_b32_e64 v61, v61, v75, s[44:45]
	v_cndmask_b32_e64 v60, v60, v74, s[44:45]
	v_cndmask_b32_e64 v59, v59, v73, s[44:45]
	v_cndmask_b32_e64 v58, v58, v72, s[44:45]
	v_cndmask_b32_e64 v57, v57, v71, s[44:45]
	v_cndmask_b32_e64 v56, v56, v70, s[44:45]
	v_lshl_add_u64 v[64:65], v[64:65], 0, v[142:143]
	s_and_b64 vcc, exec, s[48:49]
	v_cvt_pk_bf16_f32 v70, v54, v55
	v_cvt_pk_bf16_f32 v71, v56, v57
	v_cvt_pk_bf16_f32 v72, v58, v59
	v_cvt_pk_bf16_f32 v73, v60, v61
	global_store_dwordx4 v[64:65], v[70:73], off nt
	s_cbranch_vccnz .LBB0_253
	s_and_b64 s[14:15], s[50:51], s[52:53]
	s_xor_b64 s[14:15], s[14:15], -1
	s_and_saveexec_b64 s[22:23], s[14:15]
	s_xor_b64 vcc, exec, s[22:23]
	s_cbranch_execnz .LBB0_316
	s_andn2_saveexec_b64 vcc, vcc
	s_cbranch_execnz .LBB0_317

;     __device__ __forceinline__ void operator()(const f32x4 (&acc)[2][2][4][2], const Unit& u, int wr, int wc, int fr, int fq) const {
;     ...
;                     if (is_kv) {
;                         float* dst = nullptr;
;                         if (isP && t >= 4096 - W) dst = out + okp + ((size_t)(b * W + t - (4096 - W)) * 2 + kvsel) * 256 + cit;
;                         else if (isS) dst = out + oks + ((size_t)(b * W + W - 1) * 2 + kvsel) * 256 + cit;
;                         if (dst) { *(f32x4*)dst = v0; *(f32x4*)(dst + 4) = v1; }
.LBB0_251:
	global_store_dwordx4 v[66:67], v[54:57], off nt
	global_store_dwordx4 v[66:67], v[58:61], off offset:16 nt

;     __device__ __forceinline__ void operator()(const f32x4 (&acc)[2][2][4][2], const Unit& u, int wr, int wc, int fr, int fq) const {
;     ...
;                     if (is_conv) {
;                         const int cc = pn * BM + cit - ZMQ;
;                         float* dst = nullptr;
;                         if (isP && t >= 4093) dst = out + O_CONV_P + (size_t)(b * 3 + t - 4093) * 2048 + cc;
;                         else if (isS) dst = out + O_CONV_S + (size_t)(b * 3 + 2) * 2048 + cc;
;                         if (dst) { *(f32x4*)dst = v0; *(f32x4*)(dst + 4) = v1; }
.LBB0_253:
	v_lshl_add_u32 v66, v68, 1, v68
	v_ashrrev_i32_e32 v67, 31, v66
	v_lshlrev_b64 v[66:67], 13, v[66:67]
	s_mov_b64 s[14:15], 0x4000
	s_and_b64 vcc, exec, s[46:47]
	v_lshl_add_u64 v[66:67], v[66:67], 0, s[14:15]
	s_cbranch_vccnz .LBB0_257
	v_or_b32_e32 v68, s18, v158
	v_lshl_add_u64 v[70:71], s[96:97], 0, v[66:67]
	v_mov_b32_e32 v69, v143
	v_lshl_add_u64 v[68:69], v[68:69], 2, v[70:71]
	s_mov_b64 s[14:15], 0xfd35c00
	v_lshl_add_u64 v[70:71], v[68:69], 0, s[14:15]
	v_cmp_ne_u64_e32 vcc, 0, v[70:71]
	s_xor_b64 s[14:15], s[12:13], -1
	s_and_b64 s[14:15], s[14:15], vcc
	s_and_saveexec_b64 s[22:23], s[14:15]
	s_cbranch_execz .LBB0_256
	global_store_dwordx4 v[70:71], v[54:57], off nt
	s_nop 1
	v_add_co_u32_e32 v54, vcc, 0xfd35000, v68
	s_nop 1
	v_addc_co_u32_e32 v55, vcc, 0, v69, vcc
	global_store_dwordx4 v[54:55], v[58:61], off offset:3088 nt

; __device__ __forceinline__ unsigned cvt_pk_bf16(float lo, float hi) { unsigned r; asm volatile("v_cvt_pk_bf16_f32 %0, %1, %2" : "=v"(r) : "v"(lo), "v"(hi)); return r; }
;     __device__ __forceinline__ void operator()(const f32x4 (&acc)[2][2][4][2], const Unit& u, int wr, int wc, int fr, int fq) const {
;     ...
;                     f32x4 v0 = acc[ai][bj][m][0], v1 = acc[ai][bj][m][1];
;                     const int cit = bj * HALF + wc * 32 + fq * 8;
;                     if (do_rope) {
; #pragma unroll
;                         for (int j = 0; j < 4; ++j) {
;                             const float p0 = __shfl_xor(v0[j], 16), p1 = __shfl_xor(v1[j], 16);
;                             const float r0 = v0[j] * cosv[j] + sgn * p0 * sinv[j], r1 = v1[j] * cosv[4 + j] + sgn * p1 * sinv[4 + j];
;                             v0[j] = fq < 2 ? r0 : v0[j]; v1[j] = fq < 2 ? r1 : v1[j];
;                         }
;                     }
;                     if (pn < 3) { v0 = v0 * QSCALE; v1 = v1 * QSCALE; }
;                     u32x4 w; w.x = cvt_pk_bf16(v0[0], v0[1]); w.y = cvt_pk_bf16(v0[2], v0[3]); w.z = cvt_pk_bf16(v1[0], v1[1]); w.w = cvt_pk_bf16(v1[2], v1[3]);
;                     *(u32x4*)(Z + (size_t)row * NZ + pn * BM + cit) = w;
.LBB0_259:
	v_pk_mul_f32 v[54:55], v[42:43], s[8:9] op_sel_hi:[1,0]
	v_pk_mul_f32 v[56:57], v[44:45], s[8:9] op_sel_hi:[1,0]
	v_pk_mul_f32 v[58:59], v[46:47], s[8:9] op_sel_hi:[1,0]
	v_pk_mul_f32 v[60:61], v[48:49], s[8:9] op_sel_hi:[1,0]
	v_cndmask_b32_e64 v47, v47, v59, s[44:45]
	v_cndmask_b32_e64 v49, v49, v61, s[44:45]
	v_cndmask_b32_e64 v48, v48, v60, s[44:45]
	v_cndmask_b32_e64 v46, v46, v58, s[44:45]
	v_cndmask_b32_e64 v45, v45, v57, s[44:45]
	v_cndmask_b32_e64 v44, v44, v56, s[44:45]
	v_cndmask_b32_e64 v43, v43, v55, s[44:45]
	v_cndmask_b32_e64 v42, v42, v54, s[44:45]
	s_and_b64 vcc, exec, s[48:49]
	v_cvt_pk_bf16_f32 v54, v42, v43
	v_cvt_pk_bf16_f32 v55, v44, v45
	v_cvt_pk_bf16_f32 v56, v46, v47
	v_cvt_pk_bf16_f32 v57, v48, v49
	global_store_dwordx4 v[64:65], v[54:57], off offset:256 nt
	s_cbranch_vccnz .LBB0_265
	s_and_b64 s[14:15], s[50:51], s[52:53]
	s_xor_b64 s[14:15], s[14:15], -1
	s_and_saveexec_b64 s[22:23], s[14:15]
	s_xor_b64 s[50:51], exec, s[22:23]
	s_cbranch_execnz .LBB0_318
	s_andn2_saveexec_b64 s[50:51], s[50:51]
	s_cbranch_execnz .LBB0_319

;     __device__ __forceinline__ void operator()(const f32x4 (&acc)[2][2][4][2], const Unit& u, int wr, int wc, int fr, int fq) const {
;     ...
;                     if (is_kv) {
;                         float* dst = nullptr;
;                         if (isP && t >= 4096 - W) dst = out + okp + ((size_t)(b * W + t - (4096 - W)) * 2 + kvsel) * 256 + cit;
;                         else if (isS) dst = out + oks + ((size_t)(b * W + W - 1) * 2 + kvsel) * 256 + cit;
;                         if (dst) { *(f32x4*)dst = v0; *(f32x4*)(dst + 4) = v1; }
.LBB0_263:
	global_store_dwordx4 v[54:55], v[42:45], off nt
	global_store_dwordx4 v[54:55], v[46:49], off offset:16 nt

;     __device__ __forceinline__ void operator()(const f32x4 (&acc)[2][2][4][2], const Unit& u, int wr, int wc, int fr, int fq) const {
;     ...
;                     if (is_conv) {
;                         const int cc = pn * BM + cit - ZMQ;
;                         float* dst = nullptr;
;                         if (isP && t >= 4093) dst = out + O_CONV_P + (size_t)(b * 3 + t - 4093) * 2048 + cc;
;                         else if (isS) dst = out + O_CONV_S + (size_t)(b * 3 + 2) * 2048 + cc;
;                         if (dst) { *(f32x4*)dst = v0; *(f32x4*)(dst + 4) = v1; }
.LBB0_265:
	s_and_b64 vcc, exec, s[46:47]
	s_cbranch_vccnz .LBB0_269
	v_lshl_add_u64 v[52:53], s[96:97], 0, v[66:67]
	v_add_u32_e32 v54, s18, v158
	v_mov_b32_e32 v55, v143
	v_lshl_add_u64 v[52:53], v[54:55], 2, v[52:53]
	s_mov_b64 s[14:15], 0xfd35e00
	v_lshl_add_u64 v[54:55], v[52:53], 0, s[14:15]
	v_cmp_ne_u64_e32 vcc, 0, v[54:55]
	s_xor_b64 s[12:13], s[12:13], -1
	s_and_b64 s[14:15], s[12:13], vcc
	s_and_saveexec_b64 s[12:13], s[14:15]
	s_cbranch_execz .LBB0_268
	s_mov_b64 s[14:15], 0x200
	v_lshl_add_u64 v[52:53], v[52:53], 0, s[14:15]
	global_store_dwordx4 v[54:55], v[42:45], off nt
	s_nop 1
	v_add_co_u32_e32 v42, vcc, 0xfd35000, v52
	s_nop 1
	v_addc_co_u32_e32 v43, vcc, 0, v53, vcc
	global_store_dwordx4 v[42:43], v[46:49], off offset:3088 nt

; __device__ __forceinline__ unsigned cvt_pk_bf16(float lo, float hi) { unsigned r; asm volatile("v_cvt_pk_bf16_f32 %0, %1, %2" : "=v"(r) : "v"(lo), "v"(hi)); return r; }
;     __device__ __forceinline__ void operator()(const f32x4 (&acc)[2][2][4][2], const Unit& u, int wr, int wc, int fr, int fq) const {
;     ...
;                     f32x4 v0 = acc[ai][bj][m][0], v1 = acc[ai][bj][m][1];
;                     const int cit = bj * HALF + wc * 32 + fq * 8;
;                     if (do_rope) {
; #pragma unroll
;                         for (int j = 0; j < 4; ++j) {
;                             const float p0 = __shfl_xor(v0[j], 16), p1 = __shfl_xor(v1[j], 16);
;                             const float r0 = v0[j] * cosv[j] + sgn * p0 * sinv[j], r1 = v1[j] * cosv[4 + j] + sgn * p1 * sinv[4 + j];
;                             v0[j] = fq < 2 ? r0 : v0[j]; v1[j] = fq < 2 ? r1 : v1[j];
;                         }
;                     }
;                     if (pn < 3) { v0 = v0 * QSCALE; v1 = v1 * QSCALE; }
;                     u32x4 w; w.x = cvt_pk_bf16(v0[0], v0[1]); w.y = cvt_pk_bf16(v0[2], v0[3]); w.z = cvt_pk_bf16(v1[0], v1[1]); w.w = cvt_pk_bf16(v1[2], v1[3]);
;                     *(u32x4*)(Z + (size_t)row * NZ + pn * BM + cit) = w;
;                     if (is_kv) {
;                         float* dst = nullptr;
;                         if (isP && t >= 4096 - W) dst = out + okp + ((size_t)(b * W + t - (4096 - W)) * 2 + kvsel) * 256 + cit;
;                         else if (isS) dst = out + oks + ((size_t)(b * W + W - 1) * 2 + kvsel) * 256 + cit;
;                         if (dst) { *(f32x4*)dst = v0; *(f32x4*)(dst + 4) = v1; }
.LBB0_273:
	v_pk_mul_f32 v[52:53], v[34:35], s[8:9] op_sel_hi:[1,0]
	v_cmp_le_u32_e64 s[52:53], s29, v42
	v_cndmask_b32_e64 v35, v35, v53, s[44:45]
	v_cndmask_b32_e64 v34, v34, v52, s[44:45]
	v_mov_b64_e32 v[52:53], s[2:3]
	v_add_u32_e32 v42, s10, v42
	v_mad_i64_i32 v[44:45], s[12:13], v44, s9, v[52:53]
	v_ashrrev_i32_e32 v43, 31, v42
	v_pk_mul_f32 v[46:47], v[38:39], s[8:9] op_sel_hi:[1,0]
	v_pk_mul_f32 v[48:49], v[40:41], s[8:9] op_sel_hi:[1,0]
	v_pk_mul_f32 v[54:55], v[36:37], s[8:9] op_sel_hi:[1,0]
	v_lshl_add_u64 v[44:45], s[18:19], 1, v[44:45]
	v_lshlrev_b64 v[42:43], 11, v[42:43]
	v_cndmask_b32_e64 v37, v37, v55, s[44:45]
	v_cndmask_b32_e64 v36, v36, v54, s[44:45]
	v_cndmask_b32_e64 v41, v41, v49, s[44:45]
	v_cndmask_b32_e64 v40, v40, v48, s[44:45]
	v_cndmask_b32_e64 v39, v39, v47, s[44:45]
	v_cndmask_b32_e64 v38, v38, v46, s[44:45]
	v_lshl_add_u64 v[44:45], v[44:45], 0, v[142:143]
	s_and_b64 vcc, exec, s[48:49]
	v_cvt_pk_bf16_f32 v46, v38, v39
	v_cvt_pk_bf16_f32 v47, v40, v41
	v_cvt_pk_bf16_f32 v48, v34, v35
	v_cvt_pk_bf16_f32 v49, v36, v37
	global_store_dwordx4 v[44:45], v[46:49], off nt
	s_cbranch_vccnz .LBB0_277
	s_and_b64 s[12:13], s[50:51], s[52:53]
	s_lshl_b32 s11, s27, 2
	s_add_u32 s14, s96, s11
	s_addc_u32 s15, s97, 0
	v_lshl_add_u64 v[46:47], s[14:15], 0, v[42:43]
	v_lshl_add_u64 v[46:47], v[46:47], 0, s[4:5]
	v_cmp_ne_u64_e32 vcc, 0, v[46:47]
	s_and_b64 s[14:15], s[12:13], vcc
	s_and_saveexec_b64 s[12:13], s[14:15]
	s_cbranch_execz .LBB0_276
	v_lshlrev_b32_e32 v48, 2, v158
	v_mov_b32_e32 v49, v143
	v_lshl_add_u64 v[46:47], v[46:47], 0, v[48:49]
	global_store_dwordx4 v[46:47], v[38:41], off nt
	global_store_dwordx4 v[46:47], v[34:37], off offset:16 nt

; __device__ __forceinline__ unsigned cvt_pk_bf16(float lo, float hi) { unsigned r; asm volatile("v_cvt_pk_bf16_f32 %0, %1, %2" : "=v"(r) : "v"(lo), "v"(hi)); return r; }
;     __device__ __forceinline__ void operator()(const f32x4 (&acc)[2][2][4][2], const Unit& u, int wr, int wc, int fr, int fq) const {
;     ...
;                     if (pn < 3) { v0 = v0 * QSCALE; v1 = v1 * QSCALE; }
;                     u32x4 w; w.x = cvt_pk_bf16(v0[0], v0[1]); w.y = cvt_pk_bf16(v0[2], v0[3]); w.z = cvt_pk_bf16(v1[0], v1[1]); w.w = cvt_pk_bf16(v1[2], v1[3]);
;                     *(u32x4*)(Z + (size_t)row * NZ + pn * BM + cit) = w;
;                     if (is_kv) {
;                         float* dst = nullptr;
;                         if (isP && t >= 4096 - W) dst = out + okp + ((size_t)(b * W + t - (4096 - W)) * 2 + kvsel) * 256 + cit;
;                         else if (isS) dst = out + oks + ((size_t)(b * W + W - 1) * 2 + kvsel) * 256 + cit;
;                         if (dst) { *(f32x4*)dst = v0; *(f32x4*)(dst + 4) = v1; }
.LBB0_279:
	v_pk_mul_f32 v[34:35], v[30:31], s[8:9] op_sel_hi:[1,0]
	v_pk_mul_f32 v[36:37], v[32:33], s[8:9] op_sel_hi:[1,0]
	v_pk_mul_f32 v[38:39], v[26:27], s[8:9] op_sel_hi:[1,0]
	v_pk_mul_f32 v[40:41], v[28:29], s[8:9] op_sel_hi:[1,0]
	s_and_b64 s[12:13], s[92:93], s[50:51]
	v_cndmask_b32_e64 v29, v29, v41, s[44:45]
	v_cndmask_b32_e64 v28, v28, v40, s[44:45]
	v_cndmask_b32_e64 v27, v27, v39, s[44:45]
	v_cndmask_b32_e64 v26, v26, v38, s[44:45]
	v_cndmask_b32_e64 v33, v33, v37, s[44:45]
	v_cndmask_b32_e64 v32, v32, v36, s[44:45]
	v_cndmask_b32_e64 v31, v31, v35, s[44:45]
	v_cndmask_b32_e64 v30, v30, v34, s[44:45]
	s_and_b64 s[14:15], s[12:13], s[52:53]
	v_cvt_pk_bf16_f32 v34, v30, v31
	v_cvt_pk_bf16_f32 v35, v32, v33
	v_cvt_pk_bf16_f32 v36, v26, v27
	v_cvt_pk_bf16_f32 v37, v28, v29
	global_store_dwordx4 v[44:45], v[34:37], off offset:256 nt
	s_and_saveexec_b64 s[12:13], s[14:15]
	s_cbranch_execz .LBB0_281
	s_lshl_b32 s11, s27, 2
	s_add_u32 s14, s96, s11
	s_addc_u32 s15, s97, 0
	v_lshl_add_u64 v[34:35], s[14:15], 0, v[42:43]
	v_lshl_add_u64 v[34:35], v[34:35], 0, s[4:5]
	v_lshlrev_b32_e32 v36, 2, v158
	v_mov_b32_e32 v37, v143
	v_lshl_add_u64 v[34:35], v[34:35], 0, v[36:37]
	global_store_dwordx4 v[34:35], v[30:33], off offset:512 nt
	global_store_dwordx4 v[34:35], v[26:29], off offset:528 nt

; __device__ __forceinline__ unsigned cvt_pk_bf16(float lo, float hi) { unsigned r; asm volatile("v_cvt_pk_bf16_f32 %0, %1, %2" : "=v"(r) : "v"(lo), "v"(hi)); return r; }
;     __device__ __forceinline__ void operator()(const f32x4 (&acc)[2][2][4][2], const Unit& u, int wr, int wc, int fr, int fq) const {
;     ...
;                     f32x4 v0 = acc[ai][bj][m][0], v1 = acc[ai][bj][m][1];
;                     const int cit = bj * HALF + wc * 32 + fq * 8;
;                     if (do_rope) {
; #pragma unroll
;                         for (int j = 0; j < 4; ++j) {
;                             const float p0 = __shfl_xor(v0[j], 16), p1 = __shfl_xor(v1[j], 16);
;                             const float r0 = v0[j] * cosv[j] + sgn * p0 * sinv[j], r1 = v1[j] * cosv[4 + j] + sgn * p1 * sinv[4 + j];
;                             v0[j] = fq < 2 ? r0 : v0[j]; v1[j] = fq < 2 ? r1 : v1[j];
;                         }
;                     }
;                     if (pn < 3) { v0 = v0 * QSCALE; v1 = v1 * QSCALE; }
;                     u32x4 w; w.x = cvt_pk_bf16(v0[0], v0[1]); w.y = cvt_pk_bf16(v0[2], v0[3]); w.z = cvt_pk_bf16(v1[0], v1[1]); w.w = cvt_pk_bf16(v1[2], v1[3]);
;                     *(u32x4*)(Z + (size_t)row * NZ + pn * BM + cit) = w;
;                     if (is_kv) {
;                         float* dst = nullptr;
;                         if (isP && t >= 4096 - W) dst = out + okp + ((size_t)(b * W + t - (4096 - W)) * 2 + kvsel) * 256 + cit;
;                         else if (isS) dst = out + oks + ((size_t)(b * W + W - 1) * 2 + kvsel) * 256 + cit;
;                         if (dst) { *(f32x4*)dst = v0; *(f32x4*)(dst + 4) = v1; }
.LBB0_285:
	v_pk_mul_f32 v[30:31], v[18:19], s[8:9] op_sel_hi:[1,0]
	v_add_u32_e32 v26, s10, v32
	v_cndmask_b32_e64 v19, v19, v31, s[44:45]
	v_cndmask_b32_e64 v18, v18, v30, s[44:45]
	v_mov_b64_e32 v[30:31], s[2:3]
	v_mad_i64_i32 v[28:29], s[10:11], v28, s9, v[30:31]
	v_ashrrev_i32_e32 v27, 31, v26
	v_pk_mul_f32 v[34:35], v[20:21], s[8:9] op_sel_hi:[1,0]
	v_pk_mul_f32 v[36:37], v[22:23], s[8:9] op_sel_hi:[1,0]
	v_pk_mul_f32 v[38:39], v[24:25], s[8:9] op_sel_hi:[1,0]
	v_lshl_add_u64 v[28:29], s[18:19], 1, v[28:29]
	v_cmp_le_u32_e64 s[52:53], s29, v32
	v_lshlrev_b64 v[26:27], 11, v[26:27]
	v_cndmask_b32_e64 v25, v25, v39, s[44:45]
	v_cndmask_b32_e64 v24, v24, v38, s[44:45]
	v_cndmask_b32_e64 v23, v23, v37, s[44:45]
	v_cndmask_b32_e64 v22, v22, v36, s[44:45]
	v_cndmask_b32_e64 v21, v21, v35, s[44:45]
	v_cndmask_b32_e64 v20, v20, v34, s[44:45]
	v_lshl_add_u64 v[28:29], v[28:29], 0, v[142:143]
	s_and_b64 vcc, exec, s[48:49]
	v_cvt_pk_bf16_f32 v34, v18, v19
	v_cvt_pk_bf16_f32 v35, v20, v21
	v_cvt_pk_bf16_f32 v36, v22, v23
	v_cvt_pk_bf16_f32 v37, v24, v25
	global_store_dwordx4 v[28:29], v[34:37], off nt
	s_cbranch_vccnz .LBB0_289
	s_and_b64 s[10:11], s[50:51], s[52:53]
	s_lshl_b32 s12, s27, 2
	s_add_u32 s12, s96, s12
	s_addc_u32 s13, s97, 0
	v_lshl_add_u64 v[30:31], s[12:13], 0, v[26:27]
	v_lshl_add_u64 v[30:31], v[30:31], 0, s[4:5]
	v_cmp_ne_u64_e32 vcc, 0, v[30:31]
	s_and_b64 s[10:11], s[10:11], vcc
	s_and_saveexec_b64 s[12:13], s[10:11]
	s_cbranch_execz .LBB0_288
	v_lshlrev_b32_e32 v142, 2, v158
	v_lshl_add_u64 v[30:31], v[30:31], 0, v[142:143]
	global_store_dwordx4 v[30:31], v[18:21], off nt
	global_store_dwordx4 v[30:31], v[22:25], off offset:16 nt

;     __device__ __forceinline__ void operator()(const f32x4 (&acc)[2][2][4][2], const Unit& u, int wr, int wc, int fr, int fq) const {
;     ...
;                     if (is_conv) {
;                         const int cc = pn * BM + cit - ZMQ;
;                         float* dst = nullptr;
;                         if (isP && t >= 4093) dst = out + O_CONV_P + (size_t)(b * 3 + t - 4093) * 2048 + cc;
;                         else if (isS) dst = out + O_CONV_S + (size_t)(b * 3 + 2) * 2048 + cc;
;                         if (dst) { *(f32x4*)dst = v0; *(f32x4*)(dst + 4) = v1; }
.LBB0_289:
	s_mul_i32 s1, s1, 3
	s_addk_i32 s1, 0xf003
	s_movk_i32 s10, 0xffc
	v_add_u32_e32 v30, s1, v32
	v_cmp_lt_u32_e32 vcc, s10, v32
	v_ashrrev_i32_e32 v31, 31, v30
	s_and_b64 s[12:13], s[50:51], vcc
	s_and_b64 vcc, exec, s[46:47]
	v_lshlrev_b64 v[30:31], 13, v[30:31]
	s_cbranch_vccnz .LBB0_293
	v_or_b32_e32 v142, s18, v158
	v_lshl_add_u64 v[32:33], s[96:97], 0, v[30:31]
	v_lshl_add_u64 v[32:33], v[142:143], 2, v[32:33]
	s_mov_b64 s[10:11], 0xfd1dc00
	v_lshl_add_u64 v[34:35], v[32:33], 0, s[10:11]
	v_cmp_ne_u64_e32 vcc, 0, v[34:35]
	s_and_b64 s[10:11], s[12:13], vcc
	s_and_saveexec_b64 s[22:23], s[10:11]
	s_cbranch_execz .LBB0_292
	global_store_dwordx4 v[34:35], v[18:21], off nt
	s_nop 1
	v_add_co_u32_e32 v18, vcc, 0xfd1d000, v32
	s_nop 1
	v_addc_co_u32_e32 v19, vcc, 0, v33, vcc
	global_store_dwordx4 v[18:19], v[22:25], off offset:3088 nt

; __device__ __forceinline__ unsigned cvt_pk_bf16(float lo, float hi) { unsigned r; asm volatile("v_cvt_pk_bf16_f32 %0, %1, %2" : "=v"(r) : "v"(lo), "v"(hi)); return r; }
;     __device__ __forceinline__ void operator()(const f32x4 (&acc)[2][2][4][2], const Unit& u, int wr, int wc, int fr, int fq) const {
;     ...
;                     f32x4 v0 = acc[ai][bj][m][0], v1 = acc[ai][bj][m][1];
;                     const int cit = bj * HALF + wc * 32 + fq * 8;
;                     if (do_rope) {
; #pragma unroll
;                         for (int j = 0; j < 4; ++j) {
;                             const float p0 = __shfl_xor(v0[j], 16), p1 = __shfl_xor(v1[j], 16);
;                             const float r0 = v0[j] * cosv[j] + sgn * p0 * sinv[j], r1 = v1[j] * cosv[4 + j] + sgn * p1 * sinv[4 + j];
;                             v0[j] = fq < 2 ? r0 : v0[j]; v1[j] = fq < 2 ? r1 : v1[j];
;                         }
;                     }
;                     if (pn < 3) { v0 = v0 * QSCALE; v1 = v1 * QSCALE; }
;                     u32x4 w; w.x = cvt_pk_bf16(v0[0], v0[1]); w.y = cvt_pk_bf16(v0[2], v0[3]); w.z = cvt_pk_bf16(v1[0], v1[1]); w.w = cvt_pk_bf16(v1[2], v1[3]);
;                     *(u32x4*)(Z + (size_t)row * NZ + pn * BM + cit) = w;
.LBB0_295:
	v_pk_mul_f32 v[4:5], v[14:15], s[8:9] op_sel_hi:[1,0]
	v_pk_mul_f32 v[6:7], v[16:17], s[8:9] op_sel_hi:[1,0]
	v_pk_mul_f32 v[0:1], v[10:11], s[8:9] op_sel_hi:[1,0]
	v_pk_mul_f32 v[2:3], v[12:13], s[8:9] op_sel_hi:[1,0]
	s_and_b64 s[10:11], s[92:93], s[50:51]
	v_cndmask_b32_e64 v3, v13, v3, s[44:45]
	v_cndmask_b32_e64 v2, v12, v2, s[44:45]
	v_cndmask_b32_e64 v1, v11, v1, s[44:45]
	v_cndmask_b32_e64 v0, v10, v0, s[44:45]
	v_cndmask_b32_e64 v7, v17, v7, s[44:45]
	v_cndmask_b32_e64 v6, v16, v6, s[44:45]
	v_cndmask_b32_e64 v5, v15, v5, s[44:45]
	v_cndmask_b32_e64 v4, v14, v4, s[44:45]
	s_and_b64 s[10:11], s[10:11], s[52:53]
	v_cvt_pk_bf16_f32 v8, v4, v5
	v_cvt_pk_bf16_f32 v9, v6, v7
	v_cvt_pk_bf16_f32 v10, v0, v1
	v_cvt_pk_bf16_f32 v11, v2, v3
	global_store_dwordx4 v[28:29], v[8:11], off offset:256 nt
	s_and_saveexec_b64 s[42:43], s[10:11]
	s_cbranch_execnz .LBB0_298
	s_or_b64 exec, exec, s[42:43]
	s_and_b64 vcc, exec, s[46:47]
	s_cbranch_vccz .LBB0_299

;     __device__ __forceinline__ void operator()(const f32x4 (&acc)[2][2][4][2], const Unit& u, int wr, int wc, int fr, int fq) const {
;     ...
;                     if (is_kv) {
;                         float* dst = nullptr;
;                         if (isP && t >= 4096 - W) dst = out + okp + ((size_t)(b * W + t - (4096 - W)) * 2 + kvsel) * 256 + cit;
;                         else if (isS) dst = out + oks + ((size_t)(b * W + W - 1) * 2 + kvsel) * 256 + cit;
;                         if (dst) { *(f32x4*)dst = v0; *(f32x4*)(dst + 4) = v1; }
;                     }
;                     if (is_conv) {
;                         const int cc = pn * BM + cit - ZMQ;
;                         float* dst = nullptr;
;                         if (isP && t >= 4093) dst = out + O_CONV_P + (size_t)(b * 3 + t - 4093) * 2048 + cc;
;                         else if (isS) dst = out + O_CONV_S + (size_t)(b * 3 + 2) * 2048 + cc;
;                         if (dst) { *(f32x4*)dst = v0; *(f32x4*)(dst + 4) = v1; }
.LBB0_298:
	s_lshl_b32 s1, s27, 2
	s_add_u32 s10, s96, s1
	s_addc_u32 s11, s97, 0
	v_lshl_add_u64 v[8:9], s[10:11], 0, v[26:27]
	v_lshl_add_u64 v[8:9], v[8:9], 0, s[4:5]
	v_lshlrev_b32_e32 v142, 2, v158
	v_lshl_add_u64 v[8:9], v[8:9], 0, v[142:143]
	global_store_dwordx4 v[8:9], v[4:7], off offset:512 nt
	global_store_dwordx4 v[8:9], v[0:3], off offset:528 nt
	s_or_b64 exec, exec, s[42:43]
	s_and_b64 vcc, exec, s[46:47]
	s_cbranch_vccnz .LBB0_297
.LBB0_299:
	v_lshl_add_u64 v[8:9], s[96:97], 0, v[30:31]
	v_add_u32_e32 v142, s18, v158
	v_lshl_add_u64 v[8:9], v[142:143], 2, v[8:9]
	s_mov_b64 s[10:11], 0xfd1de00
	v_lshl_add_u64 v[10:11], v[8:9], 0, s[10:11]
	v_cmp_ne_u64_e32 vcc, 0, v[10:11]
	s_and_b64 s[10:11], s[12:13], vcc
	s_and_saveexec_b64 s[12:13], s[10:11]
	s_cbranch_execz .LBB0_301
	s_mov_b64 s[10:11], 0x200
	v_lshl_add_u64 v[8:9], v[8:9], 0, s[10:11]
	global_store_dwordx4 v[10:11], v[4:7], off nt
	s_nop 1
	v_add_co_u32_e32 v4, vcc, 0xfd1d000, v8
	s_nop 1
	v_addc_co_u32_e32 v5, vcc, 0, v9, vcc
	global_store_dwordx4 v[4:5], v[0:3], off offset:3088 nt
